# v10 + stick-breaking: canonicalize+min pair fused into one v_min_f32 with neg modifier (61 of the pairs, hazard-checked)
# baseline (speedup 1.0000x reference)
_Z14fwd_megakernel6Params:
	s_mov_b32 s98, 0x42700000
	s_load_dwordx8 s[4:11], s[0:1], 0x40
	s_load_dword s3, s[0:1], 0x78
	s_load_dwordx4 s[76:79], s[0:1], 0x60
	s_load_dwordx2 s[80:81], s[0:1], 0x70
	v_and_b32_e32 v1, 0x3ff, v0
	v_cmp_gt_u32_e32 vcc, 64, v1
	s_waitcnt lgkmcnt(0)
	v_writelane_b32 v254, s4, 0
	s_nop 1
	v_writelane_b32 v254, s5, 1
	v_writelane_b32 v254, s6, 2
	v_writelane_b32 v254, s7, 3
	v_writelane_b32 v254, s8, 4
	v_writelane_b32 v254, s9, 5
	v_writelane_b32 v254, s10, 6
	v_writelane_b32 v254, s11, 7
	s_add_u32 s6, s0, 0x70
	s_addc_u32 s7, s1, 0
	s_and_saveexec_b64 s[4:5], vcc
	v_lshl_add_u32 v2, v1, 2, 0
	v_add_u32_e32 v2, 0x23f00, v2
	v_mov_b32_e32 v3, 0
	ds_write_b32 v2, v3
	s_or_b64 exec, exec, s[4:5]
	s_add_u32 s4, s76, 0x12420000
	s_addc_u32 s5, s77, 0
	v_writelane_b32 v254, s4, 8
	s_waitcnt lgkmcnt(0)
	s_barrier
	v_writelane_b32 v254, s5, 9
	s_getreg_b32 s4, hwreg(HW_REG_XCC_ID, 0, 4)
	s_and_b32 s33, s4, 15
	v_cmp_eq_u32_e32 vcc, 0, v1
	s_and_saveexec_b64 s[4:5], vcc
	s_cbranch_execz .LBB0_5
	s_mov_b64 s[8:9], exec
	v_mbcnt_lo_u32_b32 v2, s8, 0
	v_mbcnt_hi_u32_b32 v2, s9, v2
	v_cmp_eq_u32_e32 vcc, 0, v2
	s_and_b64 s[10:11], exec, vcc
	s_mov_b64 exec, s[10:11]
	s_cbranch_execz .LBB0_5
	s_bcnt1_i32_b64 s8, s[8:9]
	s_lshl_b32 s10, s33, 8
	v_mov_b32_e32 v3, s8
	v_readlane_b32 s8, v254, 8
	v_mov_b32_e32 v2, s10
	v_readlane_b32 s9, v254, 9
	s_nop 4
	global_atomic_add v2, v3, s[8:9] offset:1024

.LBB0_426:
	s_bitcmp1_b32 s22, 0
	s_cselect_b32 s23, 0x2080, 0
	v_add_u32_e32 v77, s23, v196
	ds_read_b128 v[0:3], v77
	ds_read_b128 v[16:19], v229 offset:60416
	s_and_b32 s16, s39, 1
	s_mul_i32 s17, s16, 0x2080
	v_min_f32_e64 v4, -v32, s98
	v_exp_f32_e32 v24, v4
	v_max_f32_e64 v26, -v33, -v33
	v_min_f32_e32 v26, 0x42700000, v26
	v_exp_f32_e32 v26, v26
	v_add_f32_e32 v25, 1.0, v24
	v_rcp_f32_e32 v25, v25
	v_or_b32_e32 v75, s4, v197
	v_cmp_lt_i32_e32 vcc, v75, v72
	v_or_b32_e32 v27, 1, v75
	v_mul_f32_e32 v24, v24, v25
	v_cndmask_b32_e32 v32, 0, v25, vcc
	v_cndmask_b32_e32 v24, 1.0, v24, vcc
	v_cmp_lt_i32_e32 vcc, v27, v72
	v_max_f32_e64 v27, -v34, -v34
	v_add_f32_e32 v25, 1.0, v26
	v_min_f32_e32 v27, 0x42700000, v27
	v_rcp_f32_e32 v25, v25
	v_exp_f32_e32 v27, v27
	v_max_f32_e64 v28, -v35, -v35
	v_min_f32_e32 v28, 0x42700000, v28
	v_cndmask_b32_e32 v33, 0, v25, vcc
	v_mul_f32_e32 v25, v26, v25
	v_add_f32_e32 v26, 1.0, v27
	v_rcp_f32_e32 v26, v26
	v_exp_f32_e32 v28, v28
	v_cndmask_b32_e32 v73, 1.0, v25, vcc
	v_or_b32_e32 v25, 2, v75
	v_cmp_lt_i32_e32 vcc, v25, v72
	s_waitcnt lgkmcnt(0)
	v_mfma_f32_32x32x16_bf16 v[0:15], v[0:3], v[16:19], 0
	v_mul_f32_e32 v25, v27, v26
	v_cndmask_b32_e32 v34, 0, v26, vcc
	v_add_f32_e32 v26, 1.0, v28
	v_rcp_f32_e32 v26, v26
	ds_read_b128 v[20:23], v77 offset:512
	v_cndmask_b32_e32 v107, 1.0, v25, vcc
	v_or_b32_e32 v25, 3, v75
	v_cmp_lt_i32_e32 vcc, v25, v72
	v_mul_f32_e32 v25, v28, v26
	v_mul_f32_e32 v24, v24, v73
	v_cndmask_b32_e32 v108, 1.0, v25, vcc
	v_cndmask_b32_e32 v35, 0, v26, vcc
	v_mul_f32_e32 v25, v107, v108
	v_mul_f32_e32 v106, v24, v25
	v_or_b32_e32 v74, 8, v75
	v_min_f32_e64 v36, -v36, s98
	v_cmp_lt_i32_e32 vcc, v74, v72
	v_exp_f32_e32 v74, v36
	v_max_f32_e64 v37, -v37, -v37
	v_min_f32_e32 v37, 0x42700000, v37
	v_max_f32_e64 v38, -v38, -v38
	v_add_f32_e32 v36, 1.0, v74
	v_rcp_f32_e32 v76, v36
	v_min_f32_e32 v38, 0x42700000, v38
	v_max_f32_e64 v39, -v39, -v39
	v_min_f32_e32 v39, 0x42700000, v39
	v_cndmask_b32_e32 v36, 0, v76, vcc
	v_mul_f32_e32 v74, v74, v76
	v_or_b32_e32 v76, 9, v75
	v_cndmask_b32_e32 v74, 1.0, v74, vcc
	v_cmp_lt_i32_e32 vcc, v76, v72
	v_exp_f32_e32 v76, v37
	s_waitcnt lgkmcnt(0)
	v_mfma_f32_32x32x16_bf16 v[16:31], v[20:23], v[16:19], 0
	ds_read_b128 v[68:71], v77 offset:2080
	ds_read_b128 v[64:67], v229 offset:61440
	v_add_f32_e32 v37, 1.0, v76
	v_rcp_f32_e32 v78, v37
	s_nop 0
	v_mul_f32_e32 v76, v76, v78
	v_cndmask_b32_e32 v109, 1.0, v76, vcc
	v_or_b32_e32 v76, 10, v75
	v_cndmask_b32_e32 v37, 0, v78, vcc
	v_cmp_lt_i32_e32 vcc, v76, v72
	v_exp_f32_e32 v76, v38
	v_mul_f32_e32 v74, v74, v109
	v_add_f32_e32 v38, 1.0, v76
	v_rcp_f32_e32 v78, v38
	s_nop 0
	v_mul_f32_e32 v76, v76, v78
	v_cndmask_b32_e32 v110, 1.0, v76, vcc
	v_or_b32_e32 v76, 11, v75
	v_cndmask_b32_e32 v38, 0, v78, vcc
	v_cmp_lt_i32_e32 vcc, v76, v72
	v_exp_f32_e32 v76, v39
	s_nop 0
	v_add_f32_e32 v39, 1.0, v76
	v_rcp_f32_e32 v78, v39
	s_nop 0
	v_mul_f32_e32 v76, v76, v78
	v_cndmask_b32_e32 v111, 1.0, v76, vcc
	v_mul_f32_e32 v76, v110, v111
	v_cndmask_b32_e32 v39, 0, v78, vcc
	v_mul_f32_e32 v74, v74, v76
	v_min_f32_e64 v40, -v40, s98
	v_exp_f32_e32 v76, v40
	v_max_f32_e64 v41, -v41, -v41
	v_min_f32_e32 v41, 0x42700000, v41
	s_waitcnt lgkmcnt(0)
	v_mfma_f32_32x32x16_bf16 v[0:15], v[68:71], v[64:67], v[0:15]
	v_add_f32_e32 v82, 1.0, v76
	v_rcp_f32_e32 v68, v82
	v_exp_f32_e32 v69, v41
	v_or_b32_e32 v40, 16, v75
	v_cmp_lt_i32_e32 vcc, v40, v72
	v_max_f32_e64 v42, -v42, -v42
	v_mul_f32_e32 v41, v76, v68
	v_cndmask_b32_e32 v40, 0, v68, vcc
	v_add_f32_e32 v68, 1.0, v69
	v_min_f32_e32 v42, 0x42700000, v42
	v_rcp_f32_e32 v68, v68
	v_exp_f32_e32 v71, v42
	v_cndmask_b32_e32 v70, 1.0, v41, vcc
	v_or_b32_e32 v41, 17, v75
	v_cmp_lt_i32_e32 vcc, v41, v72
	v_max_f32_e64 v43, -v43, -v43
	v_mul_f32_e32 v42, v69, v68
	v_cndmask_b32_e32 v41, 0, v68, vcc
	v_add_f32_e32 v68, 1.0, v71
	v_min_f32_e32 v43, 0x42700000, v43
	v_rcp_f32_e32 v68, v68
	v_exp_f32_e32 v69, v43
	v_cndmask_b32_e32 v112, 1.0, v42, vcc
	v_or_b32_e32 v42, 18, v75
	v_cmp_lt_i32_e32 vcc, v42, v72
	v_mul_f32_e32 v43, v71, v68
	ds_read_b128 v[78:81], v77 offset:2592
	v_cndmask_b32_e32 v42, 0, v68, vcc
	v_add_f32_e32 v68, 1.0, v69
	v_rcp_f32_e32 v68, v68
	v_cndmask_b32_e32 v113, 1.0, v43, vcc
	v_or_b32_e32 v43, 19, v75
	v_cmp_lt_i32_e32 vcc, v43, v72
	s_nop 1
	v_cndmask_b32_e32 v43, 0, v68, vcc
	v_mul_f32_e32 v68, v69, v68
	v_cndmask_b32_e32 v114, 1.0, v68, vcc
	v_mul_f32_e32 v68, v70, v112
	v_mul_f32_e32 v69, v113, v114
	v_mul_f32_e32 v76, v68, v69
	v_min_f32_e64 v44, -v44, s98
	s_waitcnt lgkmcnt(0)
	v_mfma_f32_32x32x16_bf16 v[16:31], v[78:81], v[64:67], v[16:31]
	v_or_b32_e32 v64, 24, v75
	v_cmp_lt_i32_e32 vcc, v64, v72
	v_exp_f32_e32 v64, v44
	v_max_f32_e64 v45, -v45, -v45
	v_min_f32_e32 v45, 0x42700000, v45
	v_max_f32_e64 v46, -v46, -v46
	v_add_f32_e32 v44, 1.0, v64
	v_rcp_f32_e32 v65, v44
	v_min_f32_e32 v46, 0x42700000, v46
	v_max_f32_e64 v47, -v47, -v47
	v_min_f32_e32 v47, 0x42700000, v47
	v_cndmask_b32_e32 v44, 0, v65, vcc
	v_mul_f32_e32 v64, v64, v65
	v_or_b32_e32 v65, 25, v75
	v_cndmask_b32_e32 v64, 1.0, v64, vcc
	v_cmp_lt_i32_e32 vcc, v65, v72
	v_exp_f32_e32 v65, v45
	ds_read_b128 v[82:85], v77 offset:4160
	ds_read_b128 v[68:71], v229 offset:62464
	v_add_f32_e32 v45, 1.0, v65
	v_rcp_f32_e32 v66, v45
	s_nop 0
	v_mul_f32_e32 v65, v65, v66
	v_cndmask_b32_e32 v115, 1.0, v65, vcc
	v_or_b32_e32 v65, 26, v75
	v_cndmask_b32_e32 v45, 0, v66, vcc
	v_cmp_lt_i32_e32 vcc, v65, v72
	v_exp_f32_e32 v65, v46
	v_mul_f32_e32 v64, v64, v115
	v_add_f32_e32 v46, 1.0, v65
	v_rcp_f32_e32 v66, v46
	s_nop 0
	v_mul_f32_e32 v65, v65, v66
	v_cndmask_b32_e32 v148, 1.0, v65, vcc
	v_or_b32_e32 v65, 27, v75
	v_cndmask_b32_e32 v46, 0, v66, vcc
	v_cmp_lt_i32_e32 vcc, v65, v72
	v_exp_f32_e32 v65, v47
	s_nop 0
	v_add_f32_e32 v47, 1.0, v65
	v_rcp_f32_e32 v66, v47
	s_nop 0
	v_mul_f32_e32 v65, v65, v66
	v_cndmask_b32_e32 v149, 1.0, v65, vcc
	v_mul_f32_e32 v65, v148, v149
	v_cndmask_b32_e32 v47, 0, v66, vcc
	v_mul_f32_e32 v64, v64, v65
	v_min_f32_e64 v48, -v48, s98
	v_exp_f32_e32 v48, v48
	v_max_f32_e64 v49, -v49, -v49
	v_min_f32_e32 v49, 0x42700000, v49
	v_exp_f32_e32 v49, v49
	v_add_f32_e32 v66, 1.0, v48
	v_or_b32_e32 v65, 32, v75
	v_rcp_f32_e32 v66, v66
	v_max_f32_e64 v50, -v50, -v50
	v_cmp_lt_i32_e32 vcc, v65, v72
	v_add_f32_e32 v65, 1.0, v49
	v_min_f32_e32 v50, 0x42700000, v50
	v_rcp_f32_e32 v65, v65
	v_exp_f32_e32 v50, v50
	v_cndmask_b32_e32 v80, 0, v66, vcc
	v_mul_f32_e32 v48, v48, v66
	v_or_b32_e32 v66, 33, v75
	v_cndmask_b32_e32 v48, 1.0, v48, vcc
	v_cmp_lt_i32_e32 vcc, v66, v72
	v_max_f32_e64 v51, -v51, -v51
	v_mul_f32_e32 v49, v49, v65
	v_cndmask_b32_e32 v81, 0, v65, vcc
	v_add_f32_e32 v65, 1.0, v50
	v_min_f32_e32 v51, 0x42700000, v51
	v_rcp_f32_e32 v65, v65
	v_exp_f32_e32 v51, v51
	v_cndmask_b32_e32 v150, 1.0, v49, vcc
	v_or_b32_e32 v49, 34, v75
	s_waitcnt lgkmcnt(0)
	v_mfma_f32_32x32x16_bf16 v[0:15], v[82:85], v[68:71], v[0:15]
	v_cmp_lt_i32_e32 vcc, v49, v72
	v_mul_f32_e32 v49, v50, v65
	v_add_f32_e32 v50, 1.0, v51
	v_rcp_f32_e32 v50, v50
	ds_read_b128 v[86:89], v77 offset:4672
	v_cndmask_b32_e32 v151, 1.0, v49, vcc
	v_or_b32_e32 v49, 35, v75
	v_cndmask_b32_e32 v82, 0, v65, vcc
	v_cmp_lt_i32_e32 vcc, v49, v72
	v_mul_f32_e32 v49, v51, v50
	v_mul_f32_e32 v104, v48, v150
	v_cndmask_b32_e32 v152, 1.0, v49, vcc
	v_cndmask_b32_e32 v83, 0, v50, vcc
	v_mul_f32_e32 v78, v151, v152
	v_min_f32_e64 v52, -v52, s98
	v_exp_f32_e32 v52, v52
	v_or_b32_e32 v65, 40, v75
	v_cmp_lt_i32_e32 vcc, v65, v72
	s_waitcnt lgkmcnt(0)
	v_mfma_f32_32x32x16_bf16 v[16:31], v[86:89], v[68:71], v[16:31]
	v_add_f32_e32 v65, 1.0, v52
	v_rcp_f32_e32 v65, v65
	ds_read_b128 v[90:93], v77 offset:6240
	ds_read_b128 v[48:51], v229 offset:63488
	v_mul_f32_e32 v52, v52, v65
	v_cndmask_b32_e32 v68, 1.0, v52, vcc
	v_or_b32_e32 v52, 41, v75
	v_cndmask_b32_e32 v84, 0, v65, vcc
	v_cmp_lt_i32_e32 vcc, v52, v72
	v_max_f32_e64 v52, -v53, -v53
	v_min_f32_e32 v52, 0x42700000, v52
	v_exp_f32_e32 v52, v52
	s_nop 0
	v_add_f32_e32 v53, 1.0, v52
	v_rcp_f32_e32 v53, v53
	s_nop 0
	v_mul_f32_e32 v52, v52, v53
	v_cndmask_b32_e32 v66, 1.0, v52, vcc
	v_or_b32_e32 v52, 42, v75
	v_cndmask_b32_e32 v85, 0, v53, vcc
	v_cmp_lt_i32_e32 vcc, v52, v72
	v_max_f32_e64 v52, -v54, -v54
	v_min_f32_e32 v52, 0x42700000, v52
	v_exp_f32_e32 v52, v52
	s_nop 0
	v_add_f32_e32 v53, 1.0, v52
	v_rcp_f32_e32 v53, v53
	s_nop 0
	v_cndmask_b32_e32 v86, 0, v53, vcc
	v_mul_f32_e32 v52, v52, v53
	v_or_b32_e32 v53, 43, v75
	v_cndmask_b32_e32 v52, 1.0, v52, vcc
	v_cmp_lt_i32_e32 vcc, v53, v72
	v_max_f32_e64 v53, -v55, -v55
	v_min_f32_e32 v53, 0x42700000, v53
	v_exp_f32_e32 v53, v53
	s_nop 0
	v_add_f32_e32 v54, 1.0, v53
	v_rcp_f32_e32 v54, v54
	s_nop 0
	v_mul_f32_e32 v53, v53, v54
	v_cndmask_b32_e32 v87, 0, v54, vcc
	v_cndmask_b32_e32 v54, 1.0, v53, vcc
	v_min_f32_e64 v53, -v56, s98
	v_exp_f32_e32 v53, v53
	v_max_f32_e64 v57, -v57, -v57
	v_min_f32_e32 v57, 0x42700000, v57
	v_or_b32_e32 v55, 48, v75
	v_add_f32_e32 v56, 1.0, v53
	v_rcp_f32_e32 v56, v56
	v_exp_f32_e32 v57, v57
	v_cmp_lt_i32_e32 vcc, v55, v72
	s_waitcnt lgkmcnt(0)
	v_mfma_f32_32x32x16_bf16 v[0:15], v[90:93], v[48:51], v[0:15]
	v_mul_f32_e32 v53, v53, v56
	v_cndmask_b32_e32 v88, 0, v56, vcc
	v_or_b32_e32 v56, 49, v75
	v_cndmask_b32_e32 v53, 1.0, v53, vcc
	v_cmp_lt_i32_e32 vcc, v56, v72
	v_max_f32_e64 v56, -v58, -v58
	v_add_f32_e32 v55, 1.0, v57
	v_min_f32_e32 v56, 0x42700000, v56
	v_rcp_f32_e32 v55, v55
	v_exp_f32_e32 v56, v56
	v_max_f32_e64 v58, -v59, -v59
	v_min_f32_e32 v58, 0x42700000, v58
	v_cndmask_b32_e32 v89, 0, v55, vcc
	v_mul_f32_e32 v55, v57, v55
	v_add_f32_e32 v57, 1.0, v56
	v_rcp_f32_e32 v57, v57
	v_exp_f32_e32 v58, v58
	v_cndmask_b32_e32 v153, 1.0, v55, vcc
	v_or_b32_e32 v55, 50, v75
	v_cmp_lt_i32_e32 vcc, v55, v72
	v_mul_f32_e32 v55, v56, v57
	v_add_f32_e32 v56, 1.0, v58
	v_rcp_f32_e32 v56, v56
	v_cndmask_b32_e32 v158, 1.0, v55, vcc
	v_or_b32_e32 v55, 51, v75
	ds_read_b128 v[154:157], v77 offset:6752
	v_cndmask_b32_e32 v90, 0, v57, vcc
	v_cmp_lt_i32_e32 vcc, v55, v72
	v_mul_f32_e32 v55, v58, v56
	v_mul_f32_e32 v53, v53, v153
	v_cndmask_b32_e32 v159, 1.0, v55, vcc
	v_mul_f32_e32 v55, v158, v159
	v_cndmask_b32_e32 v91, 0, v56, vcc
	v_mul_f32_e32 v69, v53, v55
	s_waitcnt lgkmcnt(0)
	v_mfma_f32_32x32x16_bf16 v[16:31], v[154:157], v[48:51], v[16:31]
	v_or_b32_e32 v48, 56, v75
	v_cmp_lt_i32_e32 vcc, v48, v72
	v_max_f32_e64 v48, -v60, -v60
	v_min_f32_e32 v48, 0x42700000, v48
	v_exp_f32_e32 v48, v48
	s_nop 0
	v_add_f32_e32 v49, 1.0, v48
	v_rcp_f32_e32 v49, v49
	s_nop 0
	v_cndmask_b32_e32 v92, 0, v49, vcc
	v_mul_f32_e32 v48, v48, v49
	v_or_b32_e32 v49, 57, v75
	v_cndmask_b32_e32 v48, 1.0, v48, vcc
	v_cmp_lt_i32_e32 vcc, v49, v72
	v_max_f32_e64 v49, -v61, -v61
	v_min_f32_e32 v49, 0x42700000, v49
	v_exp_f32_e32 v49, v49
	s_nop 0
	v_add_f32_e32 v50, 1.0, v49
	v_rcp_f32_e32 v50, v50
	s_nop 0
	v_mul_f32_e32 v49, v49, v50
	v_cndmask_b32_e32 v156, 1.0, v49, vcc
	v_or_b32_e32 v49, 58, v75
	v_cndmask_b32_e32 v93, 0, v50, vcc
	v_cmp_lt_i32_e32 vcc, v49, v72
	v_max_f32_e64 v49, -v62, -v62
	v_min_f32_e32 v49, 0x42700000, v49
	v_exp_f32_e32 v49, v49
	v_mul_f32_e32 v48, v48, v156
	v_add_f32_e32 v50, 1.0, v49
	v_rcp_f32_e32 v50, v50
	s_nop 0
	v_mul_f32_e32 v49, v49, v50
	v_cndmask_b32_e32 v157, 1.0, v49, vcc
	v_or_b32_e32 v49, 59, v75
	v_cndmask_b32_e32 v94, 0, v50, vcc
	v_cmp_lt_i32_e32 vcc, v49, v72
	v_max_f32_e64 v49, -v63, -v63
	v_min_f32_e32 v49, 0x42700000, v49
	v_exp_f32_e32 v49, v49
	s_nop 0
	v_add_f32_e32 v50, 1.0, v49
	v_rcp_f32_e32 v50, v50
	s_nop 0
	v_mul_f32_e32 v49, v49, v50
	v_cndmask_b32_e32 v164, 1.0, v49, vcc
	v_mul_f32_e32 v49, v157, v164
	v_cndmask_b32_e32 v95, 0, v50, vcc
	v_mul_f32_e32 v53, v48, v49
	v_mov_b32_e32 v48, v106
	v_mov_b32_e32 v49, v106
	s_nop 1
	v_permlane32_swap_b32_e32 v48, v49
	v_cndmask_b32_e64 v165, v48, v49, s[34:35]
	v_mov_b32_e32 v48, v74
	v_mov_b32_e32 v49, v74
	s_nop 1
	v_permlane32_swap_b32_e32 v48, v49
	v_cndmask_b32_e64 v48, v48, v49, s[34:35]
	v_mov_b32_e32 v49, v76
	v_mov_b32_e32 v50, v76
	s_nop 1
	v_permlane32_swap_b32_e32 v49, v50
	v_cndmask_b32_e64 v50, v49, v50, s[34:35]
	v_mov_b32_e32 v49, v64
	v_mov_b32_e32 v51, v64
	s_nop 1
	v_permlane32_swap_b32_e32 v49, v51
	v_cndmask_b32_e64 v56, v49, v51, s[34:35]
	v_mov_b32_e32 v49, v69
	v_mov_b32_e32 v51, v69
	s_nop 1
	v_permlane32_swap_b32_e32 v49, v51
	v_cndmask_b32_e64 v67, v49, v51, s[34:35]
	v_mov_b32_e32 v49, v53
	v_mov_b32_e32 v51, v53
	s_nop 1
	v_permlane32_swap_b32_e32 v49, v51
	v_cndmask_b32_e64 v55, v49, v51, s[34:35]
	v_pk_mul_f32 v[154:155], v[52:53], v[54:55]
	v_pk_mul_f32 v[58:59], v[68:69], v[66:67]
	v_cndmask_b32_e64 v166, 1.0, v55, s[34:35]
	v_pk_mul_f32 v[58:59], v[58:59], v[154:155]
	s_nop 0
	v_mov_b32_e32 v49, v58
	v_mov_b32_e32 v51, v58
	s_nop 1
	v_permlane32_swap_b32_e32 v49, v51
	v_cndmask_b32_e64 v79, v49, v51, s[34:35]
	v_mov_b32_e32 v105, v58
	v_pk_mul_f32 v[60:61], v[104:105], v[78:79]
	v_cndmask_b32_e64 v105, 1.0, v67, s[34:35]
	v_mov_b32_e32 v49, v60
	v_mov_b32_e32 v51, v60
	s_nop 1
	v_permlane32_swap_b32_e32 v49, v51
	v_cndmask_b32_e64 v58, v49, v51, s[34:35]
	v_pk_mul_f32 v[60:61], v[60:61], v[58:59]
	v_cndmask_b32_e64 v53, 1.0, v58, s[34:35]
	v_mov_b32_e32 v65, v60
	v_mov_b32_e32 v57, v61
	v_pk_mul_f32 v[62:63], v[64:65], v[56:57]
	v_mul_f32_e32 v105, v105, v155
	v_mov_b32_e32 v77, v62
	v_mov_b32_e32 v51, v63
	v_pk_mul_f32 v[64:65], v[76:77], v[50:51]
	v_cndmask_b32_e64 v50, 1.0, v50, s[34:35]
	v_mov_b32_e32 v75, v64
	v_mov_b32_e32 v49, v65
	v_pk_mul_f32 v[70:71], v[74:75], v[48:49]
	v_cndmask_b32_e64 v49, 1.0, v165, s[34:35]
	v_mul_f32_e32 v104, v70, v71
	v_mul_f32_e32 v49, v49, v104
	v_cndmask_b32_e64 v48, 1.0, v48, s[34:35]
	v_mul_f32_e32 v55, v108, v49
	v_mul_f32_e32 v57, v107, v55
	v_mul_f32_e32 v55, v34, v55
	v_mul_f32_e32 v49, v35, v49
	v_mul_f32_e32 v48, v48, v71
	v_cvt_pk_bf16_f32 v69, v55, v49
	v_mul_f32_e32 v49, v111, v48
	v_mul_f32_e32 v58, v73, v57
	v_mul_f32_e32 v55, v110, v49
	v_mul_f32_e32 v49, v38, v49
	v_mul_f32_e32 v48, v39, v48
	v_mul_f32_e32 v58, v32, v58
	v_mul_f32_e32 v57, v33, v57
	v_cvt_pk_bf16_f32 v71, v49, v48
	v_mul_f32_e32 v48, v50, v65
	v_cvt_pk_bf16_f32 v68, v58, v57
	v_mul_f32_e32 v57, v109, v55
	v_mul_f32_e32 v49, v114, v48
	v_cndmask_b32_e64 v51, 1.0, v56, s[34:35]
	v_mul_f32_e32 v57, v36, v57
	v_mul_f32_e32 v55, v37, v55
	v_mul_f32_e32 v50, v113, v49
	v_mul_f32_e32 v49, v42, v49
	v_mul_f32_e32 v48, v43, v48
	v_cvt_pk_bf16_f32 v70, v57, v55
	v_mul_f32_e32 v55, v112, v50
	v_cvt_pk_bf16_f32 v109, v49, v48
	v_mul_f32_e32 v48, v51, v63
	v_mul_f32_e32 v55, v40, v55
	v_mul_f32_e32 v50, v41, v50
	v_mul_f32_e32 v49, v149, v48
	v_cvt_pk_bf16_f32 v108, v55, v50
	v_mul_f32_e32 v50, v148, v49
	v_mul_f32_e32 v49, v46, v49
	v_mul_f32_e32 v48, v47, v48
	v_mul_f32_e32 v51, v115, v50
	v_cvt_pk_bf16_f32 v111, v49, v48
	v_mul_f32_e32 v48, v53, v61
	v_mul_f32_e32 v51, v44, v51
	v_mul_f32_e32 v50, v45, v50
	v_mul_f32_e32 v49, v152, v48
	v_cvt_pk_bf16_f32 v110, v51, v50
	v_mul_f32_e32 v50, v151, v49
	v_mul_f32_e32 v51, v150, v50
	v_mul_f32_e32 v51, v80, v51
	v_mul_f32_e32 v50, v81, v50
	v_add_u32_e32 v107, s17, v201
	v_cvt_pk_bf16_f32 v112, v51, v50
	v_mul_f32_e32 v53, v82, v49
	v_mul_f32_e32 v55, v83, v48
	ds_read_b64_tr_b16 v[48:49], v107 offset:16640
	ds_read_b64_tr_b16 v[50:51], v107 offset:17152
	v_cndmask_b32_e64 v56, 1.0, v79, s[34:35]
	v_mul_f32_e32 v115, v56, v59
	v_mul_f32_e32 v72, v54, v115
	v_mul_f32_e32 v73, v52, v72
	v_cvt_pk_bf16_f32 v113, v53, v55
	s_waitcnt lgkmcnt(0)
	v_mfma_f32_32x32x16_bf16 v[48:63], v[68:71], v[48:51], 0
	v_mul_f32_e32 v74, v66, v73
	ds_read_b64_tr_b16 v[64:65], v107 offset:20800
	ds_read_b64_tr_b16 v[66:67], v107 offset:21312
	ds_read_b64_tr_b16 v[148:149], v107 offset:17664
	ds_read_b64_tr_b16 v[150:151], v107 offset:18176
	v_mul_f32_e32 v74, v84, v74
	v_mul_f32_e32 v73, v85, v73
	v_cvt_pk_bf16_f32 v114, v74, v73
	v_mul_f32_e32 v152, v86, v72
	s_waitcnt lgkmcnt(2)
	v_mfma_f32_32x32x16_bf16 v[64:79], v[68:71], v[64:67], 0
	v_mul_f32_e32 v115, v87, v115
	v_cvt_pk_bf16_f32 v115, v152, v115
	v_mul_f32_e32 v154, v159, v105
	v_mul_f32_e32 v152, v158, v154
	v_mul_f32_e32 v153, v153, v152
	v_mul_f32_e32 v153, v88, v153
	v_mul_f32_e32 v152, v89, v152
	s_waitcnt lgkmcnt(0)
	v_mfma_f32_32x32x16_bf16 v[48:63], v[108:111], v[148:151], v[48:63]
	ds_read_b64_tr_b16 v[148:149], v107 offset:21824
	ds_read_b64_tr_b16 v[150:151], v107 offset:22336
	v_cvt_pk_bf16_f32 v152, v153, v152
	v_mul_f32_e32 v153, v90, v154
	v_mul_f32_e32 v105, v91, v105
	v_cvt_pk_bf16_f32 v153, v153, v105
	v_mul_f32_e32 v105, v164, v166
	s_waitcnt lgkmcnt(0)
	v_mfma_f32_32x32x16_bf16 v[64:79], v[108:111], v[148:151], v[64:79]
	ds_read_b64_tr_b16 v[108:109], v107 offset:18688
	ds_read_b64_tr_b16 v[110:111], v107 offset:19200
	v_mul_f32_e32 v148, v157, v105
	v_mul_f32_e32 v149, v156, v148
	v_mul_f32_e32 v149, v92, v149
	v_mul_f32_e32 v148, v93, v148
	v_cvt_pk_bf16_f32 v154, v149, v148
	v_mul_f32_e32 v105, v94, v105
	s_waitcnt lgkmcnt(0)
	v_mfma_f32_32x32x16_bf16 v[48:63], v[112:115], v[108:111], v[48:63]
	ds_read_b64_tr_b16 v[108:109], v107 offset:22848
	ds_read_b64_tr_b16 v[110:111], v107 offset:23360
	v_mul_f32_e32 v148, v95, v166
	v_cvt_pk_bf16_f32 v155, v105, v148
	v_mul_f32_e32 v105, v106, v165
	s_waitcnt lgkmcnt(0)
	v_mfma_f32_32x32x16_bf16 v[64:79], v[112:115], v[108:111], v[64:79]
	ds_read_b64_tr_b16 v[108:109], v107 offset:19712
	ds_read_b64_tr_b16 v[110:111], v107 offset:20224
	s_waitcnt lgkmcnt(0)
	v_mfma_f32_32x32x16_bf16 v[48:63], v[152:155], v[108:111], v[48:63]
	ds_read_b64_tr_b16 v[108:109], v107 offset:23872
	ds_read_b64_tr_b16 v[110:111], v107 offset:24384
	v_mul_f32_e32 v107, v105, v104
	s_waitcnt lgkmcnt(0)
	v_mfma_f32_32x32x16_bf16 v[64:79], v[152:155], v[108:111], v[64:79]
	s_and_saveexec_b64 s[4:5], s[36:37]
	s_cbranch_execnz .LBB0_470
	s_or_b64 exec, exec, s[4:5]
	s_andn2_b64 vcc, exec, s[12:13]
	s_cbranch_vccz .LBB0_471

.LBB0_436:
	v_cmp_neq_f32_e32 vcc, 0, v107
	s_cbranch_vccz .LBB0_438
	ds_read_b128 v[32:35], v236
	ds_read_b128 v[80:83], v229 offset:60416
	v_min_f32_e64 v0, -v0, s98
	v_min_f32_e64 v1, -v1, s98
	v_min_f32_e64 v2, -v2, s98
	v_min_f32_e64 v3, -v3, s98
	v_exp_f32_e32 v108, v0
	v_exp_f32_e32 v88, v1
	v_exp_f32_e32 v110, v2
	v_exp_f32_e32 v112, v3
	s_waitcnt lgkmcnt(0)
	v_mfma_f32_32x32x16_bf16 v[32:47], v[32:35], v[80:83], 0
	ds_read_b128 v[84:87], v236 offset:512
	v_add_f32_e32 v0, 1.0, v108
	v_add_f32_e32 v1, 1.0, v88
	v_add_f32_e32 v2, 1.0, v110
	v_add_f32_e32 v3, 1.0, v112
	v_rcp_f32_e32 v0, v0
	v_rcp_f32_e32 v1, v1
	v_rcp_f32_e32 v2, v2
	v_rcp_f32_e32 v3, v3
	v_mul_f32_e32 v104, v88, v1
	v_min_f32_e64 v4, -v4, s98
	v_min_f32_e64 v5, -v5, s98
	v_min_f32_e64 v6, -v6, s98
	v_min_f32_e64 v7, -v7, s98
	v_exp_f32_e32 v114, v4
	v_exp_f32_e32 v115, v5
	v_exp_f32_e32 v148, v6
	v_exp_f32_e32 v149, v7
	s_waitcnt lgkmcnt(0)
	v_mfma_f32_32x32x16_bf16 v[80:95], v[84:87], v[80:83], 0
	v_add_f32_e32 v4, 1.0, v114
	v_add_f32_e32 v5, 1.0, v115
	v_add_f32_e32 v6, 1.0, v148
	v_add_f32_e32 v7, 1.0, v149
	ds_read_b128 v[164:167], v236 offset:2080
	ds_read_b128 v[168:171], v229 offset:61440
	v_rcp_f32_e32 v4, v4
	v_rcp_f32_e32 v5, v5
	v_rcp_f32_e32 v6, v6
	v_rcp_f32_e32 v7, v7
	v_pk_mul_f32 v[114:115], v[114:115], v[4:5]
	s_nop 0
	v_pk_mul_f32 v[156:157], v[114:115], v[114:115] op_sel_hi:[0,1]
	v_pk_mul_f32 v[150:151], v[148:149], v[6:7]
	s_nop 0
	v_pk_mul_f32 v[154:155], v[150:151], v[150:151] op_sel_hi:[0,1]
	v_min_f32_e64 v9, -v9, s98
	s_waitcnt lgkmcnt(0)
	v_mfma_f32_32x32x16_bf16 v[32:47], v[164:167], v[168:171], v[32:47]
	v_exp_f32_e32 v164, v9
	v_max_f32_e64 v8, -v8, -v8
	v_min_f32_e32 v8, 0x42700000, v8
	v_exp_f32_e32 v8, v8
	v_add_f32_e32 v9, 1.0, v164
	v_rcp_f32_e32 v152, v9
	v_max_f32_e64 v9, -v10, -v10
	v_min_f32_e32 v9, 0x42700000, v9
	v_exp_f32_e32 v9, v9
	v_add_f32_e32 v105, 1.0, v8
	v_rcp_f32_e32 v148, v105
	ds_read_b128 v[172:175], v236 offset:2592
	v_add_f32_e32 v10, 1.0, v9
	v_rcp_f32_e32 v149, v10
	v_max_f32_e64 v10, -v11, -v11
	v_min_f32_e32 v10, 0x42700000, v10
	v_exp_f32_e32 v165, v10
	v_pk_mul_f32 v[158:159], v[8:9], v[148:149]
	v_add_f32_e32 v10, 1.0, v165
	v_rcp_f32_e32 v153, v10
	s_nop 0
	v_pk_mul_f32 v[164:165], v[164:165], v[152:153]
	s_nop 0
	v_pk_mul_f32 v[8:9], v[158:159], v[164:165]
	s_nop 0
	v_pk_mul_f32 v[166:167], v[8:9], v[8:9] op_sel:[0,1] op_sel_hi:[1,0]
	v_min_f32_e64 v8, -v12, s98
	s_waitcnt lgkmcnt(0)
	v_mfma_f32_32x32x16_bf16 v[80:95], v[172:175], v[168:171], v[80:95]
	v_exp_f32_e32 v168, v8
	ds_read_b128 v[176:179], v236 offset:4160
	ds_read_b128 v[182:185], v229 offset:62464
	v_mov_b32_e32 v9, v152
	v_mov_b32_e32 v10, v149
	v_add_f32_e32 v8, 1.0, v168
	v_rcp_f32_e32 v12, v8
	v_max_f32_e64 v8, -v13, -v13
	v_min_f32_e32 v8, 0x42700000, v8
	v_exp_f32_e32 v170, v8
	v_mov_b32_e32 v172, v12
	v_mov_b32_e32 v11, v153
	v_add_f32_e32 v8, 1.0, v170
	v_rcp_f32_e32 v13, v8
	v_max_f32_e64 v8, -v14, -v14
	v_min_f32_e32 v8, 0x42700000, v8
	v_exp_f32_e32 v169, v8
	s_nop 0
	v_add_f32_e32 v8, 1.0, v169
	v_rcp_f32_e32 v14, v8
	v_max_f32_e64 v8, -v15, -v15
	v_min_f32_e32 v8, 0x42700000, v8
	v_exp_f32_e32 v171, v8
	v_mov_b32_e32 v173, v14
	v_pk_mul_f32 v[168:169], v[168:169], v[172:173]
	v_mov_b32_e32 v172, v13
	v_add_f32_e32 v8, 1.0, v171
	v_rcp_f32_e32 v15, v8
	v_mov_b32_e32 v8, v148
	v_mov_b32_e32 v173, v15
	v_pk_mul_f32 v[170:171], v[170:171], v[172:173]
	s_nop 0
	v_pk_mul_f32 v[172:173], v[168:169], v[170:171]
	s_nop 0
	v_mul_f32_e32 v105, v172, v173
	v_min_f32_e64 v17, -v17, s98
	v_exp_f32_e32 v106, v17
	v_max_f32_e64 v16, -v16, -v16
	v_max_f32_e64 v18, -v18, -v18
	v_add_f32_e32 v17, 1.0, v106
	v_rcp_f32_e32 v17, v17
	v_min_f32_e32 v16, 0x42700000, v16
	v_min_f32_e32 v18, 0x42700000, v18
	v_min_f32_e64 v19, -v19, s98
	s_waitcnt lgkmcnt(0)
	v_mfma_f32_32x32x16_bf16 v[32:47], v[176:179], v[182:185], v[32:47]
	v_exp_f32_e32 v176, v16
	v_mul_f32_e32 v172, v106, v17
	v_exp_f32_e32 v180, v18
	v_exp_f32_e32 v106, v19
	v_add_f32_e32 v16, 1.0, v176
	ds_read_b128 v[186:189], v236 offset:4672
	v_add_f32_e32 v18, 1.0, v180
	v_add_f32_e32 v19, 1.0, v106
	v_rcp_f32_e32 v16, v16
	v_rcp_f32_e32 v18, v18
	v_rcp_f32_e32 v19, v19
	v_min_f32_e64 v20, -v20, s98
	v_min_f32_e64 v21, -v21, s98
	v_min_f32_e64 v22, -v22, s98
	v_min_f32_e64 v23, -v23, s98
	v_exp_f32_e32 v174, v20
	v_exp_f32_e32 v175, v21
	v_exp_f32_e32 v178, v22
	v_exp_f32_e32 v179, v23
	s_waitcnt lgkmcnt(0)
	v_mfma_f32_32x32x16_bf16 v[80:95], v[186:189], v[182:185], v[80:95]
	v_add_f32_e32 v20, 1.0, v174
	v_add_f32_e32 v21, 1.0, v175
	v_add_f32_e32 v22, 1.0, v178
	v_add_f32_e32 v23, 1.0, v179
	ds_read_b128 v[238:241], v236 offset:6240
	ds_read_b128 v[242:245], v229 offset:63488
	v_rcp_f32_e32 v20, v20
	v_rcp_f32_e32 v21, v21
	v_rcp_f32_e32 v22, v22
	v_rcp_f32_e32 v23, v23
	v_pk_mul_f32 v[174:175], v[174:175], v[20:21]
	s_nop 0
	v_pk_mul_f32 v[250:251], v[174:175], v[174:175] op_sel_hi:[0,1]
	v_pk_mul_f32 v[178:179], v[178:179], v[22:23]
	s_nop 0
	v_pk_mul_f32 v[252:253], v[178:179], v[178:179] op_sel_hi:[0,1]
	v_min_f32_e64 v25, -v25, s98
	v_exp_f32_e32 v188, v25
	v_max_f32_e64 v24, -v24, -v24
	v_min_f32_e32 v24, 0x42700000, v24
	v_exp_f32_e32 v24, v24
	v_add_f32_e32 v25, 1.0, v188
	v_rcp_f32_e32 v184, v25
	v_max_f32_e64 v25, -v26, -v26
	v_min_f32_e32 v25, 0x42700000, v25
	v_exp_f32_e32 v25, v25
	s_waitcnt lgkmcnt(0)
	v_mfma_f32_32x32x16_bf16 v[32:47], v[238:241], v[242:245], v[32:47]
	v_add_f32_e32 v109, 1.0, v24
	v_rcp_f32_e32 v182, v109
	v_add_f32_e32 v26, 1.0, v25
	v_rcp_f32_e32 v183, v26
	v_max_f32_e64 v26, -v27, -v27
	v_min_f32_e32 v26, 0x42700000, v26
	v_exp_f32_e32 v189, v26
	ds_read_b128 v[246:249], v236 offset:6752
	v_pk_mul_f32 v[186:187], v[24:25], v[182:183]
	v_add_f32_e32 v26, 1.0, v189
	v_rcp_f32_e32 v185, v26
	s_nop 0
	v_pk_mul_f32 v[188:189], v[188:189], v[184:185]
	s_nop 0
	v_pk_mul_f32 v[24:25], v[186:187], v[188:189]
	s_nop 0
	v_pk_mul_f32 v[238:239], v[24:25], v[24:25] op_sel:[0,1] op_sel_hi:[1,0]
	v_min_f32_e64 v24, -v28, s98
	v_exp_f32_e32 v240, v24
	s_waitcnt lgkmcnt(0)
	v_mfma_f32_32x32x16_bf16 v[80:95], v[246:249], v[242:245], v[80:95]
	v_mov_b32_e32 v25, v184
	v_mov_b32_e32 v26, v183
	v_add_f32_e32 v24, 1.0, v240
	v_rcp_f32_e32 v28, v24
	v_max_f32_e64 v24, -v29, -v29
	v_min_f32_e32 v24, 0x42700000, v24
	v_exp_f32_e32 v242, v24
	v_mov_b32_e32 v244, v28
	v_mov_b32_e32 v27, v185
	v_add_f32_e32 v24, 1.0, v242
	v_rcp_f32_e32 v29, v24
	v_max_f32_e64 v24, -v30, -v30
	v_min_f32_e32 v24, 0x42700000, v24
	v_exp_f32_e32 v241, v24
	s_nop 0
	v_add_f32_e32 v24, 1.0, v241
	v_rcp_f32_e32 v30, v24
	v_max_f32_e64 v24, -v31, -v31
	v_min_f32_e32 v24, 0x42700000, v24
	v_exp_f32_e32 v243, v24
	v_mov_b32_e32 v245, v30
	v_pk_mul_f32 v[244:245], v[240:241], v[244:245]
	v_mov_b32_e32 v240, v29
	v_add_f32_e32 v24, 1.0, v243
	v_rcp_f32_e32 v31, v24
	v_mov_b32_e32 v24, v182
	v_mov_b32_e32 v241, v31
	v_pk_mul_f32 v[242:243], v[242:243], v[240:241]
	s_nop 0
	v_pk_mul_f32 v[240:241], v[244:245], v[242:243]
	s_nop 0
	v_mul_f32_e32 v109, v240, v241
	v_mov_b32_e32 v111, v166
	v_mov_b32_e32 v113, v166
	s_nop 1
	v_permlane32_swap_b32_e32 v111, v113
	v_cndmask_b32_e64 v167, v111, v113, s[34:35]
	v_mov_b32_e32 v111, v105
	v_mov_b32_e32 v113, v105
	s_nop 1
	v_permlane32_swap_b32_e32 v111, v113
	v_cndmask_b32_e64 v114, v111, v113, s[34:35]
	v_mov_b32_e32 v111, v238
	v_mov_b32_e32 v113, v238
	s_nop 1
	v_permlane32_swap_b32_e32 v111, v113
	v_cndmask_b32_e64 v239, v111, v113, s[34:35]
	v_mov_b32_e32 v111, v109
	v_mov_b32_e32 v113, v109
	s_nop 1
	v_permlane32_swap_b32_e32 v111, v113
	v_mov_b32_e32 v177, v251
	v_mov_b32_e32 v252, v16
	v_cndmask_b32_e64 v156, v111, v113, s[34:35]
	v_pk_mul_f32 v[176:177], v[176:177], v[252:253]
	v_mul_f32_e32 v241, v109, v156
	v_mov_b32_e32 v109, v177
	v_mov_b32_e32 v111, v177
	s_nop 1
	v_permlane32_swap_b32_e32 v109, v111
	v_mov_b32_e32 v240, v19
	v_mov_b32_e32 v181, v238
	v_mov_b32_e32 v238, v18
	v_cndmask_b32_e64 v173, v109, v111, s[34:35]
	v_pk_mul_f32 v[246:247], v[106:107], v[240:241]
	v_pk_mul_f32 v[180:181], v[180:181], v[238:239]
	v_pk_mul_f32 v[176:177], v[176:177], v[172:173]
	v_pk_mul_f32 v[248:249], v[180:181], v[246:247]
	v_mov_b32_e32 v154, v0
	v_pk_mul_f32 v[176:177], v[176:177], v[248:249]
	v_mul_f32_e32 v113, v105, v114
	v_mov_b32_e32 v106, v176
	v_mov_b32_e32 v109, v176
	s_nop 1
	v_permlane32_swap_b32_e32 v106, v109
	v_cndmask_b32_e64 v106, v106, v109, s[34:35]
	v_mul_f32_e32 v109, v176, v106
	v_mul_f32_e32 v251, v109, v177
	v_mov_b32_e32 v109, v157
	v_pk_mul_f32 v[108:109], v[108:109], v[154:155]
	v_mov_b32_e32 v250, v3
	v_mov_b32_e32 v105, v109
	v_mov_b32_e32 v111, v109
	s_nop 1
	v_permlane32_swap_b32_e32 v105, v111
	v_cndmask_b32_e64 v105, v105, v111, s[34:35]
	v_mov_b32_e32 v111, v166
	v_mov_b32_e32 v166, v2
	v_pk_mul_f32 v[112:113], v[112:113], v[250:251]
	v_pk_mul_f32 v[110:111], v[110:111], v[166:167]
	v_pk_mul_f32 v[108:109], v[108:109], v[104:105]
	v_pk_mul_f32 v[154:155], v[110:111], v[112:113]
	v_cndmask_b32_e64 v166, 1.0, v239, s[34:35]
	v_pk_mul_f32 v[108:109], v[108:109], v[154:155]
	v_cndmask_b32_e64 v157, 1.0, v167, s[34:35]
	v_mov_b32_e32 v111, v108
	v_mov_b32_e32 v154, v108
	s_nop 1
	v_permlane32_swap_b32_e32 v111, v154
	v_cndmask_b32_e64 v111, v111, v154, s[34:35]
	v_mul_f32_e32 v108, v108, v111
	v_mul_f32_e32 v154, v108, v109
	v_cndmask_b32_e64 v108, 1.0, v111, s[34:35]
	v_mul_f32_e32 v109, v108, v109
	v_mul_f32_e32 v108, v112, v109
	v_cndmask_b32_e64 v111, 1.0, v105, s[34:35]
	v_mul_f32_e32 v105, v110, v108
	v_mul_f32_e32 v104, v104, v105
	v_pk_mul_f32 v[104:105], v[0:1], v[104:105]
	v_mov_b32_e32 v110, v148
	v_cvt_pk_bf16_f32 v238, v104, v105
	v_pk_mul_f32 v[104:105], v[2:3], v[108:109]
	v_cndmask_b32_e64 v114, 1.0, v114, s[34:35]
	v_cvt_pk_bf16_f32 v239, v104, v105
	v_mul_f32_e32 v105, v111, v155
	v_mul_f32_e32 v104, v151, v105
	v_mul_f32_e32 v109, v150, v104
	v_pk_mul_f32 v[104:105], v[6:7], v[104:105]
	v_mul_f32_e32 v108, v115, v109
	v_cvt_pk_bf16_f32 v241, v104, v105
	v_mul_f32_e32 v105, v157, v113
	v_pk_mul_f32 v[108:109], v[4:5], v[108:109]
	v_mul_f32_e32 v104, v165, v105
	v_cvt_pk_bf16_f32 v240, v108, v109
	v_mul_f32_e32 v109, v159, v104
	v_mul_f32_e32 v108, v164, v109
	v_mov_b32_e32 v111, v152
	v_mov_b32_e32 v152, v149
	v_pk_mul_f32 v[108:109], v[110:111], v[108:109]
	v_pk_mul_f32 v[104:105], v[152:153], v[104:105]
	v_cvt_pk_bf16_f32 v108, v108, v109
	v_cvt_pk_bf16_f32 v109, v104, v105
	v_mul_f32_e32 v105, v114, v251
	v_mul_f32_e32 v104, v171, v105
	v_mul_f32_e32 v111, v169, v104
	v_mul_f32_e32 v110, v170, v111
	v_cndmask_b32_e64 v106, 1.0, v106, s[34:35]
	v_pk_mul_f32 v[110:111], v[12:13], v[110:111]
	v_pk_mul_f32 v[104:105], v[14:15], v[104:105]
	v_cvt_pk_bf16_f32 v110, v110, v111
	v_cvt_pk_bf16_f32 v111, v104, v105
	v_mul_f32_e32 v105, v106, v177
	v_mul_f32_e32 v104, v246, v105
	v_mul_f32_e32 v113, v180, v104
	v_mul_f32_e32 v112, v172, v113
	v_cndmask_b32_e64 v158, 1.0, v173, s[34:35]
	v_pk_mul_f32 v[112:113], v[16:17], v[112:113]
	v_pk_mul_f32 v[104:105], v[18:19], v[104:105]
	v_cvt_pk_bf16_f32 v112, v112, v113
	v_cvt_pk_bf16_f32 v113, v104, v105
	v_mul_f32_e32 v105, v158, v249
	v_mul_f32_e32 v104, v179, v105
	v_mul_f32_e32 v115, v178, v104
	v_mul_f32_e32 v114, v175, v115
	v_mul_f32_e32 v149, v166, v247
	v_pk_mul_f32 v[114:115], v[20:21], v[114:115]
	v_pk_mul_f32 v[104:105], v[22:23], v[104:105]
	v_mul_f32_e32 v148, v189, v149
	v_cvt_pk_bf16_f32 v114, v114, v115
	v_cvt_pk_bf16_f32 v115, v104, v105
	v_mul_f32_e32 v105, v187, v148
	v_mul_f32_e32 v104, v188, v105
	v_mov_b32_e32 v150, v182
	v_mov_b32_e32 v151, v184
	v_mov_b32_e32 v184, v183
	v_cndmask_b32_e64 v156, 1.0, v156, s[34:35]
	v_pk_mul_f32 v[104:105], v[150:151], v[104:105]
	v_pk_mul_f32 v[148:149], v[184:185], v[148:149]
	v_cvt_pk_bf16_f32 v104, v104, v105
	v_cvt_pk_bf16_f32 v105, v148, v149
	v_mul_f32_e32 v149, v107, v156
	v_mul_f32_e32 v148, v243, v149
	v_mul_f32_e32 v107, v245, v148
	v_mul_f32_e32 v106, v242, v107
	v_pk_mul_f32 v[106:107], v[28:29], v[106:107]
	v_pk_mul_f32 v[148:149], v[30:31], v[148:149]
	v_add_u32_e32 v152, s53, v201
	v_cvt_pk_bf16_f32 v106, v106, v107
	v_cvt_pk_bf16_f32 v107, v148, v149
	ds_read_b64_tr_b16 v[148:149], v152 offset:16640
	ds_read_b64_tr_b16 v[150:151], v152 offset:17152
	s_waitcnt lgkmcnt(0)
	v_mfma_f32_32x32x16_bf16 v[48:63], v[238:241], v[148:151], v[48:63]
	ds_read_b64_tr_b16 v[148:149], v152 offset:20800
	ds_read_b64_tr_b16 v[150:151], v152 offset:21312
	s_waitcnt lgkmcnt(0)
	v_mfma_f32_32x32x16_bf16 v[64:79], v[238:241], v[148:151], v[64:79]
	ds_read_b64_tr_b16 v[148:149], v152 offset:17664
	ds_read_b64_tr_b16 v[150:151], v152 offset:18176
	s_waitcnt lgkmcnt(0)
	v_mfma_f32_32x32x16_bf16 v[48:63], v[108:111], v[148:151], v[48:63]
	ds_read_b64_tr_b16 v[148:149], v152 offset:21824
	ds_read_b64_tr_b16 v[150:151], v152 offset:22336
	s_waitcnt lgkmcnt(0)
	v_mfma_f32_32x32x16_bf16 v[64:79], v[108:111], v[148:151], v[64:79]
	ds_read_b64_tr_b16 v[108:109], v152 offset:18688
	ds_read_b64_tr_b16 v[110:111], v152 offset:19200
	s_waitcnt lgkmcnt(0)
	v_mfma_f32_32x32x16_bf16 v[48:63], v[112:115], v[108:111], v[48:63]
	ds_read_b64_tr_b16 v[108:109], v152 offset:22848
	ds_read_b64_tr_b16 v[110:111], v152 offset:23360
	s_waitcnt lgkmcnt(0)
	v_mfma_f32_32x32x16_bf16 v[64:79], v[112:115], v[108:111], v[64:79]
	ds_read_b64_tr_b16 v[108:109], v152 offset:19712
	ds_read_b64_tr_b16 v[110:111], v152 offset:20224
	s_waitcnt lgkmcnt(0)
	v_mfma_f32_32x32x16_bf16 v[48:63], v[104:107], v[108:111], v[48:63]
	ds_read_b64_tr_b16 v[108:109], v152 offset:23872
	ds_read_b64_tr_b16 v[110:111], v152 offset:24384
	s_waitcnt lgkmcnt(0)
	v_mfma_f32_32x32x16_bf16 v[64:79], v[104:107], v[108:111], v[64:79]
	v_mov_b32_e32 v107, v154

.LBB0_447:
	v_cmp_neq_f32_e32 vcc, 0, v107
	s_cbranch_vccz .LBB0_449
	v_add_u32_e32 v105, s53, v196
	ds_read_b128 v[0:3], v105
	ds_read_b128 v[16:19], v229 offset:60416
	v_max_f32_e64 v24, -v32, -v32
	v_min_f32_e32 v24, 0x42700000, v24
	v_exp_f32_e32 v108, v24
	s_waitcnt lgkmcnt(0)
	v_mfma_f32_32x32x16_bf16 v[0:15], v[0:3], v[16:19], 0
	ds_read_b128 v[20:23], v105 offset:512
	v_add_f32_e32 v24, 1.0, v108
	v_rcp_f32_e32 v32, v24
	v_max_f32_e64 v24, -v33, -v33
	v_min_f32_e32 v24, 0x42700000, v24
	v_exp_f32_e32 v24, v24
	s_nop 0
	v_add_f32_e32 v25, 1.0, v24
	v_rcp_f32_e32 v33, v25
	s_nop 0
	v_mul_f32_e32 v104, v24, v33
	v_min_f32_e64 v24, -v34, s98
	v_exp_f32_e32 v110, v24
	s_nop 0
	v_add_f32_e32 v24, 1.0, v110
	v_rcp_f32_e32 v34, v24
	v_max_f32_e64 v24, -v35, -v35
	v_min_f32_e32 v24, 0x42700000, v24
	v_exp_f32_e32 v112, v24
	s_nop 0
	v_add_f32_e32 v24, 1.0, v112
	v_rcp_f32_e32 v35, v24
	v_min_f32_e64 v36, -v36, s98
	v_min_f32_e64 v37, -v37, s98
	v_min_f32_e64 v38, -v38, s98
	v_min_f32_e64 v39, -v39, s98
	v_exp_f32_e32 v114, v36
	v_exp_f32_e32 v115, v37
	v_exp_f32_e32 v148, v38
	v_exp_f32_e32 v149, v39
	s_waitcnt lgkmcnt(0)
	v_mfma_f32_32x32x16_bf16 v[16:31], v[20:23], v[16:19], 0
	v_add_f32_e32 v36, 1.0, v114
	v_add_f32_e32 v37, 1.0, v115
	v_add_f32_e32 v38, 1.0, v148
	v_add_f32_e32 v39, 1.0, v149
	ds_read_b128 v[164:167], v105 offset:2080
	ds_read_b128 v[168:171], v229 offset:61440
	v_rcp_f32_e32 v36, v36
	v_rcp_f32_e32 v37, v37
	v_rcp_f32_e32 v38, v38
	v_rcp_f32_e32 v39, v39
	v_pk_mul_f32 v[114:115], v[114:115], v[36:37]
	s_nop 0
	v_pk_mul_f32 v[156:157], v[114:115], v[114:115] op_sel_hi:[0,1]
	v_pk_mul_f32 v[150:151], v[148:149], v[38:39]
	s_nop 0
	v_pk_mul_f32 v[154:155], v[150:151], v[150:151] op_sel_hi:[0,1]
	v_min_f32_e64 v41, -v41, s98
	s_waitcnt lgkmcnt(0)
	v_mfma_f32_32x32x16_bf16 v[0:15], v[164:167], v[168:171], v[0:15]
	v_exp_f32_e32 v164, v41
	v_max_f32_e64 v40, -v40, -v40
	v_min_f32_e32 v40, 0x42700000, v40
	v_exp_f32_e32 v40, v40
	v_add_f32_e32 v41, 1.0, v164
	v_rcp_f32_e32 v152, v41
	v_max_f32_e64 v41, -v42, -v42
	v_min_f32_e32 v41, 0x42700000, v41
	v_exp_f32_e32 v41, v41
	v_add_f32_e32 v106, 1.0, v40
	v_rcp_f32_e32 v148, v106
	ds_read_b128 v[172:175], v105 offset:2592
	v_add_f32_e32 v42, 1.0, v41
	v_rcp_f32_e32 v149, v42
	v_max_f32_e64 v42, -v43, -v43
	v_min_f32_e32 v42, 0x42700000, v42
	v_exp_f32_e32 v165, v42
	v_pk_mul_f32 v[158:159], v[40:41], v[148:149]
	v_add_f32_e32 v42, 1.0, v165
	v_rcp_f32_e32 v153, v42
	s_nop 0
	v_pk_mul_f32 v[164:165], v[164:165], v[152:153]
	s_nop 0
	v_pk_mul_f32 v[40:41], v[158:159], v[164:165]
	s_nop 0
	v_pk_mul_f32 v[166:167], v[40:41], v[40:41] op_sel:[0,1] op_sel_hi:[1,0]
	v_min_f32_e64 v40, -v44, s98
	s_waitcnt lgkmcnt(0)
	v_mfma_f32_32x32x16_bf16 v[16:31], v[172:175], v[168:171], v[16:31]
	v_exp_f32_e32 v168, v40
	ds_read_b128 v[176:179], v105 offset:4160
	ds_read_b128 v[182:185], v229 offset:62464
	v_mov_b32_e32 v41, v152
	v_mov_b32_e32 v42, v149
	v_add_f32_e32 v40, 1.0, v168
	v_rcp_f32_e32 v44, v40
	v_max_f32_e64 v40, -v45, -v45
	v_min_f32_e32 v40, 0x42700000, v40
	v_exp_f32_e32 v170, v40
	v_mov_b32_e32 v172, v44
	v_mov_b32_e32 v43, v153
	v_add_f32_e32 v40, 1.0, v170
	v_rcp_f32_e32 v45, v40
	v_max_f32_e64 v40, -v46, -v46
	v_min_f32_e32 v40, 0x42700000, v40
	v_exp_f32_e32 v169, v40
	s_nop 0
	v_add_f32_e32 v40, 1.0, v169
	v_rcp_f32_e32 v46, v40
	v_max_f32_e64 v40, -v47, -v47
	v_min_f32_e32 v40, 0x42700000, v40
	v_exp_f32_e32 v171, v40
	v_mov_b32_e32 v173, v46
	v_pk_mul_f32 v[168:169], v[168:169], v[172:173]
	v_mov_b32_e32 v172, v45
	v_add_f32_e32 v40, 1.0, v171
	v_rcp_f32_e32 v47, v40
	v_mov_b32_e32 v40, v148
	v_mov_b32_e32 v173, v47
	v_pk_mul_f32 v[170:171], v[170:171], v[172:173]
	s_nop 0
	v_pk_mul_f32 v[172:173], v[168:169], v[170:171]
	s_nop 0
	v_mul_f32_e32 v109, v172, v173
	v_min_f32_e64 v81, -v81, s98
	v_exp_f32_e32 v106, v81
	v_max_f32_e64 v80, -v80, -v80
	v_max_f32_e64 v82, -v82, -v82
	v_add_f32_e32 v81, 1.0, v106
	v_rcp_f32_e32 v81, v81
	v_min_f32_e32 v80, 0x42700000, v80
	v_min_f32_e32 v82, 0x42700000, v82
	v_min_f32_e64 v83, -v83, s98
	s_waitcnt lgkmcnt(0)
	v_mfma_f32_32x32x16_bf16 v[0:15], v[176:179], v[182:185], v[0:15]
	v_exp_f32_e32 v176, v80
	v_mul_f32_e32 v172, v106, v81
	v_exp_f32_e32 v180, v82
	v_exp_f32_e32 v106, v83
	v_add_f32_e32 v80, 1.0, v176
	ds_read_b128 v[186:189], v105 offset:4672
	v_add_f32_e32 v82, 1.0, v180
	v_add_f32_e32 v83, 1.0, v106
	v_rcp_f32_e32 v80, v80
	v_rcp_f32_e32 v82, v82
	v_rcp_f32_e32 v83, v83
	v_min_f32_e64 v84, -v84, s98
	v_min_f32_e64 v85, -v85, s98
	v_min_f32_e64 v86, -v86, s98
	v_min_f32_e64 v87, -v87, s98
	v_exp_f32_e32 v174, v84
	v_exp_f32_e32 v175, v85
	v_exp_f32_e32 v178, v86
	v_exp_f32_e32 v179, v87
	s_waitcnt lgkmcnt(0)
	v_mfma_f32_32x32x16_bf16 v[16:31], v[186:189], v[182:185], v[16:31]
	v_add_f32_e32 v84, 1.0, v174
	v_add_f32_e32 v85, 1.0, v175
	v_add_f32_e32 v86, 1.0, v178
	v_add_f32_e32 v87, 1.0, v179
	ds_read_b128 v[238:241], v105 offset:6240
	ds_read_b128 v[242:245], v229 offset:63488
	v_rcp_f32_e32 v84, v84
	v_rcp_f32_e32 v85, v85
	v_rcp_f32_e32 v86, v86
	v_rcp_f32_e32 v87, v87
	v_pk_mul_f32 v[174:175], v[174:175], v[84:85]
	s_nop 0
	v_pk_mul_f32 v[250:251], v[174:175], v[174:175] op_sel_hi:[0,1]
	v_pk_mul_f32 v[178:179], v[178:179], v[86:87]
	s_nop 0
	v_pk_mul_f32 v[252:253], v[178:179], v[178:179] op_sel_hi:[0,1]
	v_min_f32_e64 v89, -v89, s98
	v_exp_f32_e32 v188, v89
	v_max_f32_e64 v88, -v88, -v88
	v_min_f32_e32 v88, 0x42700000, v88
	v_exp_f32_e32 v88, v88
	v_add_f32_e32 v89, 1.0, v188
	v_rcp_f32_e32 v184, v89
	v_max_f32_e64 v89, -v90, -v90
	v_min_f32_e32 v89, 0x42700000, v89
	v_exp_f32_e32 v89, v89
	s_waitcnt lgkmcnt(0)
	v_mfma_f32_32x32x16_bf16 v[0:15], v[238:241], v[242:245], v[0:15]
	ds_read_b128 v[246:249], v105 offset:6752
	v_add_f32_e32 v105, 1.0, v88
	v_add_f32_e32 v90, 1.0, v89
	v_rcp_f32_e32 v183, v90
	v_max_f32_e64 v90, -v91, -v91
	v_min_f32_e32 v90, 0x42700000, v90
	v_exp_f32_e32 v189, v90
	v_rcp_f32_e32 v182, v105
	v_add_f32_e32 v90, 1.0, v189
	v_rcp_f32_e32 v185, v90
	v_pk_mul_f32 v[186:187], v[88:89], v[182:183]
	v_pk_mul_f32 v[188:189], v[188:189], v[184:185]
	s_nop 0
	v_pk_mul_f32 v[88:89], v[186:187], v[188:189]
	s_nop 0
	v_pk_mul_f32 v[238:239], v[88:89], v[88:89] op_sel:[0,1] op_sel_hi:[1,0]
	v_min_f32_e64 v88, -v92, s98
	v_exp_f32_e32 v240, v88
	s_waitcnt lgkmcnt(0)
	v_mfma_f32_32x32x16_bf16 v[16:31], v[246:249], v[242:245], v[16:31]
	v_mov_b32_e32 v89, v184
	v_mov_b32_e32 v90, v183
	v_add_f32_e32 v88, 1.0, v240
	v_rcp_f32_e32 v92, v88
	v_max_f32_e64 v88, -v93, -v93
	v_min_f32_e32 v88, 0x42700000, v88
	v_exp_f32_e32 v242, v88
	v_mov_b32_e32 v244, v92
	v_mov_b32_e32 v91, v185
	v_add_f32_e32 v88, 1.0, v242
	v_rcp_f32_e32 v93, v88
	v_max_f32_e64 v88, -v94, -v94
	v_min_f32_e32 v88, 0x42700000, v88
	v_exp_f32_e32 v241, v88
	s_nop 0
	v_add_f32_e32 v88, 1.0, v241
	v_rcp_f32_e32 v94, v88
	v_max_f32_e64 v88, -v95, -v95
	v_min_f32_e32 v88, 0x42700000, v88
	v_exp_f32_e32 v243, v88
	v_mov_b32_e32 v245, v94
	v_pk_mul_f32 v[244:245], v[240:241], v[244:245]
	v_mov_b32_e32 v240, v93
	v_add_f32_e32 v88, 1.0, v243
	v_rcp_f32_e32 v95, v88
	v_mov_b32_e32 v88, v182
	v_mov_b32_e32 v241, v95
	v_pk_mul_f32 v[242:243], v[242:243], v[240:241]
	s_nop 0
	v_pk_mul_f32 v[240:241], v[244:245], v[242:243]
	s_nop 0
	v_mul_f32_e32 v105, v240, v241
	v_mov_b32_e32 v111, v166
	v_mov_b32_e32 v113, v166
	s_nop 1
	v_permlane32_swap_b32_e32 v111, v113
	v_cndmask_b32_e64 v167, v111, v113, s[34:35]
	v_mov_b32_e32 v111, v109
	v_mov_b32_e32 v113, v109
	s_nop 1
	v_permlane32_swap_b32_e32 v111, v113
	v_cndmask_b32_e64 v114, v111, v113, s[34:35]
	v_mov_b32_e32 v111, v238
	v_mov_b32_e32 v113, v238
	s_nop 1
	v_permlane32_swap_b32_e32 v111, v113
	v_cndmask_b32_e64 v239, v111, v113, s[34:35]
	v_mov_b32_e32 v111, v105
	v_mov_b32_e32 v113, v105
	s_nop 1
	v_permlane32_swap_b32_e32 v111, v113
	v_mov_b32_e32 v177, v251
	v_mov_b32_e32 v252, v80
	v_cndmask_b32_e64 v156, v111, v113, s[34:35]
	v_pk_mul_f32 v[176:177], v[176:177], v[252:253]
	v_mul_f32_e32 v241, v105, v156
	v_mov_b32_e32 v105, v177
	v_mov_b32_e32 v111, v177
	s_nop 1
	v_permlane32_swap_b32_e32 v105, v111
	v_mov_b32_e32 v240, v83
	v_mov_b32_e32 v181, v238
	v_mov_b32_e32 v238, v82
	v_cndmask_b32_e64 v173, v105, v111, s[34:35]
	v_pk_mul_f32 v[246:247], v[106:107], v[240:241]
	v_pk_mul_f32 v[180:181], v[180:181], v[238:239]
	v_pk_mul_f32 v[176:177], v[176:177], v[172:173]
	v_pk_mul_f32 v[248:249], v[180:181], v[246:247]
	v_mul_f32_e32 v113, v109, v114
	v_pk_mul_f32 v[176:177], v[176:177], v[248:249]
	v_mov_b32_e32 v109, v157
	v_mov_b32_e32 v105, v176
	v_mov_b32_e32 v106, v176
	s_nop 1
	v_permlane32_swap_b32_e32 v105, v106
	v_cndmask_b32_e64 v106, v105, v106, s[34:35]
	v_mov_b32_e32 v154, v32
	v_mul_f32_e32 v105, v176, v106
	v_pk_mul_f32 v[108:109], v[108:109], v[154:155]
	v_mul_f32_e32 v251, v105, v177
	v_mov_b32_e32 v105, v109
	v_mov_b32_e32 v111, v109
	s_nop 1
	v_permlane32_swap_b32_e32 v105, v111
	v_cndmask_b32_e64 v105, v105, v111, s[34:35]
	v_mov_b32_e32 v250, v35
	v_mov_b32_e32 v111, v166
	v_mov_b32_e32 v166, v34
	v_pk_mul_f32 v[112:113], v[112:113], v[250:251]
	v_pk_mul_f32 v[110:111], v[110:111], v[166:167]
	v_pk_mul_f32 v[108:109], v[108:109], v[104:105]
	v_pk_mul_f32 v[154:155], v[110:111], v[112:113]
	v_cndmask_b32_e64 v166, 1.0, v239, s[34:35]
	v_pk_mul_f32 v[108:109], v[108:109], v[154:155]
	v_cndmask_b32_e64 v157, 1.0, v167, s[34:35]
	v_mov_b32_e32 v111, v108
	v_mov_b32_e32 v154, v108
	s_nop 1
	v_permlane32_swap_b32_e32 v111, v154
	v_cndmask_b32_e64 v111, v111, v154, s[34:35]
	v_mul_f32_e32 v108, v108, v111
	v_mul_f32_e32 v154, v108, v109
	v_cndmask_b32_e64 v108, 1.0, v111, s[34:35]
	v_mul_f32_e32 v109, v108, v109
	v_mul_f32_e32 v108, v112, v109
	v_cndmask_b32_e64 v111, 1.0, v105, s[34:35]
	v_mul_f32_e32 v105, v110, v108
	v_mul_f32_e32 v104, v104, v105
	v_pk_mul_f32 v[104:105], v[32:33], v[104:105]
	v_mov_b32_e32 v110, v148
	v_cvt_pk_bf16_f32 v238, v104, v105
	v_pk_mul_f32 v[104:105], v[34:35], v[108:109]
	v_cndmask_b32_e64 v114, 1.0, v114, s[34:35]
	v_cvt_pk_bf16_f32 v239, v104, v105
	v_mul_f32_e32 v105, v111, v155
	v_mul_f32_e32 v104, v151, v105
	v_mul_f32_e32 v109, v150, v104
	v_pk_mul_f32 v[104:105], v[38:39], v[104:105]
	v_mul_f32_e32 v108, v115, v109
	v_cvt_pk_bf16_f32 v241, v104, v105
	v_mul_f32_e32 v105, v157, v113
	v_pk_mul_f32 v[108:109], v[36:37], v[108:109]
	v_mul_f32_e32 v104, v165, v105
	v_cvt_pk_bf16_f32 v240, v108, v109
	v_mul_f32_e32 v109, v159, v104
	v_mul_f32_e32 v108, v164, v109
	v_mov_b32_e32 v111, v152
	v_mov_b32_e32 v152, v149
	v_pk_mul_f32 v[108:109], v[110:111], v[108:109]
	v_pk_mul_f32 v[104:105], v[152:153], v[104:105]
	v_cvt_pk_bf16_f32 v108, v108, v109
	v_cvt_pk_bf16_f32 v109, v104, v105
	v_mul_f32_e32 v105, v114, v251
	v_mul_f32_e32 v104, v171, v105
	v_mul_f32_e32 v111, v169, v104
	v_mul_f32_e32 v110, v170, v111
	v_cndmask_b32_e64 v106, 1.0, v106, s[34:35]
	v_pk_mul_f32 v[110:111], v[44:45], v[110:111]
	v_pk_mul_f32 v[104:105], v[46:47], v[104:105]
	v_cvt_pk_bf16_f32 v110, v110, v111
	v_cvt_pk_bf16_f32 v111, v104, v105
	v_mul_f32_e32 v105, v106, v177
	v_mul_f32_e32 v104, v246, v105
	v_mul_f32_e32 v113, v180, v104
	v_mul_f32_e32 v112, v172, v113
	v_cndmask_b32_e64 v158, 1.0, v173, s[34:35]
	v_pk_mul_f32 v[112:113], v[80:81], v[112:113]
	v_pk_mul_f32 v[104:105], v[82:83], v[104:105]
	v_cvt_pk_bf16_f32 v112, v112, v113
	v_cvt_pk_bf16_f32 v113, v104, v105
	v_mul_f32_e32 v105, v158, v249
	v_mul_f32_e32 v104, v179, v105
	v_mul_f32_e32 v115, v178, v104
	v_mul_f32_e32 v114, v175, v115
	v_mul_f32_e32 v149, v166, v247
	v_pk_mul_f32 v[114:115], v[84:85], v[114:115]
	v_pk_mul_f32 v[104:105], v[86:87], v[104:105]
	v_mul_f32_e32 v148, v189, v149
	v_cvt_pk_bf16_f32 v114, v114, v115
	v_cvt_pk_bf16_f32 v115, v104, v105
	v_mul_f32_e32 v105, v187, v148
	v_mul_f32_e32 v104, v188, v105
	v_mov_b32_e32 v150, v182
	v_mov_b32_e32 v151, v184
	v_mov_b32_e32 v184, v183
	v_cndmask_b32_e64 v156, 1.0, v156, s[34:35]
	v_pk_mul_f32 v[104:105], v[150:151], v[104:105]
	v_pk_mul_f32 v[148:149], v[184:185], v[148:149]
	v_cvt_pk_bf16_f32 v104, v104, v105
	v_cvt_pk_bf16_f32 v105, v148, v149
	v_mul_f32_e32 v149, v107, v156
	v_mul_f32_e32 v148, v243, v149
	v_mul_f32_e32 v107, v245, v148
	v_mul_f32_e32 v106, v242, v107
	v_pk_mul_f32 v[106:107], v[92:93], v[106:107]
	v_pk_mul_f32 v[148:149], v[94:95], v[148:149]
	v_cvt_pk_bf16_f32 v106, v106, v107
	v_cvt_pk_bf16_f32 v107, v148, v149
	ds_read_b64_tr_b16 v[148:149], v237 offset:16640
	ds_read_b64_tr_b16 v[150:151], v237 offset:17152
	s_waitcnt lgkmcnt(0)
	v_mfma_f32_32x32x16_bf16 v[48:63], v[238:241], v[148:151], v[48:63]
	ds_read_b64_tr_b16 v[148:149], v237 offset:20800
	ds_read_b64_tr_b16 v[150:151], v237 offset:21312
	s_waitcnt lgkmcnt(0)
	v_mfma_f32_32x32x16_bf16 v[64:79], v[238:241], v[148:151], v[64:79]
	ds_read_b64_tr_b16 v[148:149], v237 offset:17664
	ds_read_b64_tr_b16 v[150:151], v237 offset:18176
	s_waitcnt lgkmcnt(0)
	v_mfma_f32_32x32x16_bf16 v[48:63], v[108:111], v[148:151], v[48:63]
	ds_read_b64_tr_b16 v[148:149], v237 offset:21824
	ds_read_b64_tr_b16 v[150:151], v237 offset:22336
	s_waitcnt lgkmcnt(0)
	v_mfma_f32_32x32x16_bf16 v[64:79], v[108:111], v[148:151], v[64:79]
	ds_read_b64_tr_b16 v[108:109], v237 offset:18688
	ds_read_b64_tr_b16 v[110:111], v237 offset:19200
	s_waitcnt lgkmcnt(0)
	v_mfma_f32_32x32x16_bf16 v[48:63], v[112:115], v[108:111], v[48:63]
	ds_read_b64_tr_b16 v[108:109], v237 offset:22848
	ds_read_b64_tr_b16 v[110:111], v237 offset:23360
	s_waitcnt lgkmcnt(0)
	v_mfma_f32_32x32x16_bf16 v[64:79], v[112:115], v[108:111], v[64:79]
	ds_read_b64_tr_b16 v[108:109], v237 offset:19712
	ds_read_b64_tr_b16 v[110:111], v237 offset:20224
	s_waitcnt lgkmcnt(0)
	v_mfma_f32_32x32x16_bf16 v[48:63], v[104:107], v[108:111], v[48:63]
	ds_read_b64_tr_b16 v[108:109], v237 offset:23872
	ds_read_b64_tr_b16 v[110:111], v237 offset:24384
	s_waitcnt lgkmcnt(0)
	v_mfma_f32_32x32x16_bf16 v[64:79], v[104:107], v[108:111], v[64:79]
	v_mov_b32_e32 v107, v154

.LBB0_461:
	s_and_b32 s17, s22, 1
	s_mul_i32 s16, s17, 0x2080
	v_cmp_neq_f32_e32 vcc, 0, v107
	s_cbranch_vccz .LBB0_463
	v_max_f32_e64 v0, -v0, -v0
	v_min_f32_e32 v0, 0x42700000, v0
	v_exp_f32_e32 v40, v0
	v_max_f32_e64 v0, -v1, -v1
	v_min_f32_e32 v0, 0x42700000, v0
	v_exp_f32_e32 v1, v0
	v_max_f32_e64 v2, -v2, -v2
	v_min_f32_e32 v2, 0x42700000, v2
	v_exp_f32_e32 v38, v2
	v_min_f32_e64 v2, -v3, s98
	v_add_f32_e32 v0, 1.0, v40
	v_rcp_f32_e32 v32, v0
	v_add_f32_e32 v0, 1.0, v1
	v_exp_f32_e32 v44, v2
	v_rcp_f32_e32 v168, v0
	v_add_f32_e32 v0, 1.0, v38
	v_rcp_f32_e32 v2, v0
	v_add_f32_e32 v0, 1.0, v44
	v_rcp_f32_e32 v0, v0
	v_mul_f32_e32 v34, v1, v168
	v_min_f32_e64 v1, -v4, s98
	v_exp_f32_e32 v36, v1
	v_min_f32_e64 v1, -v5, s98
	v_min_f32_e64 v3, -v6, s98
	v_exp_f32_e32 v37, v1
	v_exp_f32_e32 v42, v3
	v_max_f32_e64 v3, -v7, -v7
	v_min_f32_e32 v3, 0x42700000, v3
	v_exp_f32_e32 v43, v3
	v_add_f32_e32 v1, 1.0, v36
	v_rcp_f32_e32 v4, v1
	v_add_f32_e32 v1, 1.0, v37
	v_rcp_f32_e32 v5, v1
	v_add_f32_e32 v1, 1.0, v42
	v_rcp_f32_e32 v6, v1
	v_add_f32_e32 v1, 1.0, v43
	v_rcp_f32_e32 v7, v1
	v_pk_mul_f32 v[36:37], v[36:37], v[4:5]
	v_pk_mul_f32 v[42:43], v[42:43], v[6:7]
	v_pk_mul_f32 v[92:93], v[36:37], v[36:37] op_sel_hi:[0,1]
	v_pk_mul_f32 v[90:91], v[42:43], v[42:43] op_sel_hi:[0,1]
	v_min_f32_e64 v1, -v8, s98
	v_exp_f32_e32 v46, v1
	v_min_f32_e64 v1, -v9, s98
	v_min_f32_e64 v3, -v10, s98
	v_exp_f32_e32 v80, v1
	v_exp_f32_e32 v47, v3
	v_max_f32_e64 v3, -v11, -v11
	v_min_f32_e32 v3, 0x42700000, v3
	v_exp_f32_e32 v81, v3
	v_add_f32_e32 v1, 1.0, v46
	v_rcp_f32_e32 v8, v1
	v_add_f32_e32 v1, 1.0, v80
	v_rcp_f32_e32 v10, v1
	v_add_f32_e32 v1, 1.0, v47
	v_rcp_f32_e32 v9, v1
	v_add_f32_e32 v1, 1.0, v81
	v_rcp_f32_e32 v11, v1
	v_pk_mul_f32 v[46:47], v[46:47], v[8:9]
	v_pk_mul_f32 v[80:81], v[80:81], v[10:11]
	s_nop 0
	v_pk_mul_f32 v[82:83], v[46:47], v[80:81]
	s_nop 0
	v_pk_mul_f32 v[108:109], v[82:83], v[82:83] op_sel:[0,1] op_sel_hi:[1,0]
	v_min_f32_e64 v1, -v12, s98
	v_exp_f32_e32 v82, v1
	v_min_f32_e64 v1, -v13, s98
	v_min_f32_e64 v3, -v14, s98
	v_exp_f32_e32 v84, v1
	v_exp_f32_e32 v83, v3
	v_max_f32_e64 v3, -v15, -v15
	v_min_f32_e32 v3, 0x42700000, v3
	v_exp_f32_e32 v85, v3
	v_add_f32_e32 v1, 1.0, v82
	v_rcp_f32_e32 v12, v1
	v_add_f32_e32 v1, 1.0, v84
	v_rcp_f32_e32 v14, v1
	v_add_f32_e32 v1, 1.0, v83
	v_rcp_f32_e32 v13, v1
	v_add_f32_e32 v1, 1.0, v85
	v_rcp_f32_e32 v15, v1
	v_pk_mul_f32 v[82:83], v[82:83], v[12:13]
	v_pk_mul_f32 v[84:85], v[84:85], v[14:15]
	s_nop 0
	v_pk_mul_f32 v[86:87], v[82:83], v[84:85]
	s_nop 0
	v_mul_f32_e32 v33, v86, v87
	v_min_f32_e64 v1, -v16, s98
	v_exp_f32_e32 v110, v1
	v_max_f32_e64 v1, -v17, -v17
	v_min_f32_e32 v1, 0x42700000, v1
	v_exp_f32_e32 v1, v1
	v_max_f32_e64 v17, -v18, -v18
	v_min_f32_e32 v17, 0x42700000, v17
	v_exp_f32_e32 v112, v17
	v_min_f32_e64 v17, -v19, s98
	v_add_f32_e32 v3, 1.0, v110
	v_rcp_f32_e32 v16, v3
	v_add_f32_e32 v3, 1.0, v1
	v_exp_f32_e32 v106, v17
	v_rcp_f32_e32 v36, v3
	v_add_f32_e32 v3, 1.0, v112
	v_rcp_f32_e32 v18, v3
	v_add_f32_e32 v3, 1.0, v106
	v_rcp_f32_e32 v86, v3
	v_mul_f32_e32 v88, v1, v36
	v_min_f32_e64 v1, -v20, s98
	v_exp_f32_e32 v94, v1
	v_min_f32_e64 v1, -v21, s98
	v_min_f32_e64 v3, -v22, s98
	v_exp_f32_e32 v95, v1
	v_exp_f32_e32 v104, v3
	v_max_f32_e64 v3, -v23, -v23
	v_min_f32_e32 v3, 0x42700000, v3
	v_exp_f32_e32 v105, v3
	v_add_f32_e32 v1, 1.0, v94
	v_rcp_f32_e32 v20, v1
	v_add_f32_e32 v1, 1.0, v95
	v_rcp_f32_e32 v21, v1
	v_add_f32_e32 v1, 1.0, v104
	v_rcp_f32_e32 v22, v1
	v_add_f32_e32 v1, 1.0, v105
	v_rcp_f32_e32 v23, v1
	v_pk_mul_f32 v[94:95], v[94:95], v[20:21]
	v_pk_mul_f32 v[104:105], v[104:105], v[22:23]
	v_pk_mul_f32 v[114:115], v[94:95], v[94:95] op_sel_hi:[0,1]
	v_pk_mul_f32 v[148:149], v[104:105], v[104:105] op_sel_hi:[0,1]
	v_min_f32_e64 v1, -v24, s98
	v_exp_f32_e32 v150, v1
	v_min_f32_e64 v1, -v25, s98
	v_min_f32_e64 v3, -v26, s98
	v_exp_f32_e32 v152, v1
	v_exp_f32_e32 v151, v3
	v_max_f32_e64 v3, -v27, -v27
	v_min_f32_e32 v3, 0x42700000, v3
	v_exp_f32_e32 v153, v3
	v_add_f32_e32 v1, 1.0, v150
	v_rcp_f32_e32 v24, v1
	v_add_f32_e32 v1, 1.0, v152
	v_rcp_f32_e32 v154, v1
	v_add_f32_e32 v1, 1.0, v151
	v_rcp_f32_e32 v25, v1
	v_add_f32_e32 v1, 1.0, v153
	v_rcp_f32_e32 v155, v1
	v_pk_mul_f32 v[26:27], v[150:151], v[24:25]
	v_pk_mul_f32 v[150:151], v[152:153], v[154:155]
	s_nop 0
	v_pk_mul_f32 v[152:153], v[26:27], v[150:151]
	s_nop 0
	v_pk_mul_f32 v[152:153], v[152:153], v[152:153] op_sel:[0,1] op_sel_hi:[1,0]
	v_min_f32_e64 v1, -v28, s98
	v_exp_f32_e32 v28, v1
	v_min_f32_e64 v1, -v29, s98
	v_min_f32_e64 v3, -v30, s98
	v_exp_f32_e32 v156, v1
	v_exp_f32_e32 v29, v3
	v_max_f32_e64 v3, -v31, -v31
	v_min_f32_e32 v3, 0x42700000, v3
	v_exp_f32_e32 v157, v3
	v_add_f32_e32 v1, 1.0, v28
	v_rcp_f32_e32 v158, v1
	v_add_f32_e32 v1, 1.0, v156
	v_rcp_f32_e32 v164, v1
	v_add_f32_e32 v1, 1.0, v29
	v_rcp_f32_e32 v159, v1
	v_add_f32_e32 v1, 1.0, v157
	v_rcp_f32_e32 v165, v1
	v_pk_mul_f32 v[166:167], v[28:29], v[158:159]
	v_pk_mul_f32 v[156:157], v[156:157], v[164:165]
	s_nop 0
	v_pk_mul_f32 v[28:29], v[166:167], v[156:157]
	s_nop 0
	v_mul_f32_e32 v1, v28, v29
	v_mov_b32_e32 v3, v108
	v_mov_b32_e32 v17, v108
	s_nop 1
	v_permlane32_swap_b32_e32 v3, v17
	v_cndmask_b32_e64 v3, v3, v17, s[34:35]
	v_mov_b32_e32 v17, v33
	v_mov_b32_e32 v19, v33
	s_nop 1
	v_permlane32_swap_b32_e32 v17, v19
	v_cndmask_b32_e64 v46, v17, v19, s[34:35]
	v_mov_b32_e32 v17, v152
	v_mov_b32_e32 v19, v152
	s_nop 1
	v_permlane32_swap_b32_e32 v17, v19
	v_cndmask_b32_e64 v19, v17, v19, s[34:35]
	v_mov_b32_e32 v17, v1
	v_mov_b32_e32 v26, v1
	s_nop 1
	v_permlane32_swap_b32_e32 v17, v26
	v_cndmask_b32_e64 v82, v17, v26, s[34:35]
	v_mov_b32_e32 v111, v115
	v_mov_b32_e32 v17, v149
	v_pk_mul_f32 v[28:29], v[110:111], v[16:17]
	v_mul_f32_e32 v87, v1, v82
	v_mov_b32_e32 v1, v29
	v_mov_b32_e32 v17, v29
	s_nop 1
	v_permlane32_swap_b32_e32 v1, v17
	v_mov_b32_e32 v113, v152
	v_cndmask_b32_e64 v89, v1, v17, s[34:35]
	v_pk_mul_f32 v[110:111], v[106:107], v[86:87]
	v_pk_mul_f32 v[112:113], v[112:113], v[18:19]
	v_pk_mul_f32 v[28:29], v[28:29], v[88:89]
	v_pk_mul_f32 v[114:115], v[112:113], v[110:111]
	v_mul_f32_e32 v45, v33, v46
	v_pk_mul_f32 v[148:149], v[28:29], v[114:115]
	v_mov_b32_e32 v41, v93
	v_mov_b32_e32 v1, v148
	v_mov_b32_e32 v17, v148
	s_nop 1
	v_permlane32_swap_b32_e32 v1, v17
	v_mov_b32_e32 v33, v91
	v_cndmask_b32_e64 v17, v1, v17, s[34:35]
	v_pk_mul_f32 v[28:29], v[40:41], v[32:33]
	v_mul_f32_e32 v1, v148, v17
	v_mov_b32_e32 v26, v29
	v_mov_b32_e32 v30, v29
	v_mul_f32_e32 v1, v1, v149
	s_nop 0
	v_permlane32_swap_b32_e32 v26, v30
	v_mov_b32_e32 v39, v108
	v_cndmask_b32_e64 v35, v26, v30, s[34:35]
	v_pk_mul_f32 v[40:41], v[44:45], v[0:1]
	v_pk_mul_f32 v[30:31], v[38:39], v[2:3]
	v_pk_mul_f32 v[28:29], v[28:29], v[34:35]
	v_pk_mul_f32 v[38:39], v[30:31], v[40:41]
	v_mov_b32_e32 v33, v168
	v_pk_mul_f32 v[28:29], v[28:29], v[38:39]
	v_cndmask_b32_e64 v38, 1.0, v46, s[34:35]
	v_mov_b32_e32 v26, v28
	v_mov_b32_e32 v31, v28
	s_nop 1
	v_permlane32_swap_b32_e32 v26, v31
	v_cndmask_b32_e64 v31, v26, v31, s[34:35]
	v_mul_f32_e32 v26, v28, v31
	v_cndmask_b32_e64 v28, 1.0, v31, s[34:35]
	v_mul_f32_e32 v45, v28, v29
	v_mul_f32_e32 v44, v40, v45
	v_mul_f32_e32 v26, v26, v29
	v_mul_f32_e32 v29, v30, v44
	v_cndmask_b32_e64 v31, 1.0, v35, s[34:35]
	v_cndmask_b32_e64 v35, 1.0, v3, s[34:35]
	v_mul_f32_e32 v28, v34, v29
	v_mov_b32_e32 v3, v0
	v_pk_mul_f32 v[28:29], v[32:33], v[28:29]
	v_pk_mul_f32 v[2:3], v[2:3], v[44:45]
	v_cvt_pk_bf16_f32 v28, v28, v29
	v_cvt_pk_bf16_f32 v29, v2, v3
	v_mul_f32_e32 v3, v31, v39
	v_mul_f32_e32 v2, v43, v3
	v_mul_f32_e32 v31, v42, v2
	v_mul_f32_e32 v30, v37, v31
	v_pk_mul_f32 v[2:3], v[6:7], v[2:3]
	v_pk_mul_f32 v[4:5], v[4:5], v[30:31]
	v_cvt_pk_bf16_f32 v31, v2, v3
	v_mul_f32_e32 v3, v35, v41
	v_mul_f32_e32 v2, v81, v3
	v_cvt_pk_bf16_f32 v30, v4, v5
	v_mul_f32_e32 v5, v47, v2
	v_mul_f32_e32 v4, v80, v5
	v_mov_b32_e32 v6, v8
	v_mov_b32_e32 v7, v10
	v_mov_b32_e32 v10, v9
	v_mul_f32_e32 v1, v38, v1
	v_pk_mul_f32 v[4:5], v[6:7], v[4:5]
	v_pk_mul_f32 v[2:3], v[10:11], v[2:3]
	v_mul_f32_e32 v0, v85, v1
	v_cvt_pk_bf16_f32 v4, v4, v5
	v_cvt_pk_bf16_f32 v5, v2, v3
	v_mul_f32_e32 v3, v83, v0
	v_mov_b32_e32 v7, v14
	v_mov_b32_e32 v14, v13
	v_cndmask_b32_e64 v17, 1.0, v17, s[34:35]
	v_mul_f32_e32 v2, v84, v3
	v_mov_b32_e32 v6, v12
	v_pk_mul_f32 v[0:1], v[14:15], v[0:1]
	v_pk_mul_f32 v[2:3], v[6:7], v[2:3]
	v_cvt_pk_bf16_f32 v7, v0, v1
	v_mul_f32_e32 v1, v17, v149
	v_cndmask_b32_e64 v87, 1.0, v19, s[34:35]
	v_mul_f32_e32 v0, v110, v1
	v_mov_b32_e32 v19, v86
	v_cndmask_b32_e64 v46, 1.0, v89, s[34:35]
	v_cvt_pk_bf16_f32 v6, v2, v3
	v_mul_f32_e32 v3, v112, v0
	v_pk_mul_f32 v[0:1], v[18:19], v[0:1]
	v_mul_f32_e32 v2, v88, v3
	v_mov_b32_e32 v17, v36
	v_cvt_pk_bf16_f32 v9, v0, v1
	v_mul_f32_e32 v1, v46, v115
	v_pk_mul_f32 v[2:3], v[16:17], v[2:3]
	v_mul_f32_e32 v0, v105, v1
	v_cvt_pk_bf16_f32 v8, v2, v3
	v_mul_f32_e32 v3, v104, v0
	v_mul_f32_e32 v2, v95, v3
	v_pk_mul_f32 v[2:3], v[20:21], v[2:3]
	v_pk_mul_f32 v[0:1], v[22:23], v[0:1]
	v_cvt_pk_bf16_f32 v10, v2, v3
	v_mul_f32_e32 v3, v87, v111
	v_mul_f32_e32 v2, v151, v3
	v_cvt_pk_bf16_f32 v11, v0, v1
	v_mul_f32_e32 v1, v27, v2
	v_cndmask_b32_e64 v82, 1.0, v82, s[34:35]
	v_mul_f32_e32 v0, v150, v1
	v_mov_b32_e32 v12, v24
	v_mov_b32_e32 v13, v154
	v_pk_mul_f32 v[0:1], v[12:13], v[0:1]
	v_mov_b32_e32 v154, v25
	v_mul_f32_e32 v13, v107, v82
	v_pk_mul_f32 v[2:3], v[154:155], v[2:3]
	v_mul_f32_e32 v12, v157, v13
	v_cvt_pk_bf16_f32 v0, v0, v1
	v_cvt_pk_bf16_f32 v1, v2, v3
	v_mul_f32_e32 v3, v167, v12
	v_mul_f32_e32 v2, v156, v3
	v_mov_b32_e32 v14, v158
	v_mov_b32_e32 v15, v164
	v_mov_b32_e32 v164, v159
	v_pk_mul_f32 v[2:3], v[14:15], v[2:3]
	v_pk_mul_f32 v[12:13], v[164:165], v[12:13]
	v_add_u32_e32 v16, s16, v201
	v_cvt_pk_bf16_f32 v2, v2, v3
	v_cvt_pk_bf16_f32 v3, v12, v13
	ds_read_b64_tr_b16 v[12:13], v16 offset:16640
	ds_read_b64_tr_b16 v[14:15], v16 offset:17152
	s_waitcnt lgkmcnt(0)
	v_mfma_f32_32x32x16_bf16 v[48:63], v[28:31], v[12:15], v[48:63]
	ds_read_b64_tr_b16 v[12:13], v16 offset:20800
	ds_read_b64_tr_b16 v[14:15], v16 offset:21312
	v_mov_b32_e32 v107, v26
	s_waitcnt lgkmcnt(0)
	v_mfma_f32_32x32x16_bf16 v[64:79], v[28:31], v[12:15], v[64:79]
	ds_read_b64_tr_b16 v[12:13], v16 offset:17664
	ds_read_b64_tr_b16 v[14:15], v16 offset:18176
	s_waitcnt lgkmcnt(0)
	v_mfma_f32_32x32x16_bf16 v[48:63], v[4:7], v[12:15], v[48:63]
	ds_read_b64_tr_b16 v[12:13], v16 offset:21824
	ds_read_b64_tr_b16 v[14:15], v16 offset:22336
	s_waitcnt lgkmcnt(0)
	v_mfma_f32_32x32x16_bf16 v[64:79], v[4:7], v[12:15], v[64:79]
	ds_read_b64_tr_b16 v[4:5], v16 offset:18688
	ds_read_b64_tr_b16 v[6:7], v16 offset:19200
	s_waitcnt lgkmcnt(0)
	v_mfma_f32_32x32x16_bf16 v[48:63], v[8:11], v[4:7], v[48:63]
	ds_read_b64_tr_b16 v[4:5], v16 offset:22848
	ds_read_b64_tr_b16 v[6:7], v16 offset:23360
	s_waitcnt lgkmcnt(0)
	v_mfma_f32_32x32x16_bf16 v[64:79], v[8:11], v[4:7], v[64:79]
	ds_read_b64_tr_b16 v[4:5], v16 offset:19712
	ds_read_b64_tr_b16 v[6:7], v16 offset:20224
	s_waitcnt lgkmcnt(0)
	v_mfma_f32_32x32x16_bf16 v[48:63], v[0:3], v[4:7], v[48:63]
	ds_read_b64_tr_b16 v[4:5], v16 offset:23872
	ds_read_b64_tr_b16 v[6:7], v16 offset:24384
	s_waitcnt lgkmcnt(0)
	v_mfma_f32_32x32x16_bf16 v[64:79], v[0:3], v[4:7], v[64:79]

	.amdhsa_kernel _Z14fwd_megakernel6Params
		.amdhsa_group_segment_fixed_size 0
		.amdhsa_private_segment_fixed_size 0
		.amdhsa_kernarg_size 368
		.amdhsa_user_sgpr_count 2
		.amdhsa_user_sgpr_dispatch_ptr 0
		.amdhsa_user_sgpr_queue_ptr 0
		.amdhsa_user_sgpr_kernarg_segment_ptr 1
		.amdhsa_user_sgpr_dispatch_id 0
		.amdhsa_user_sgpr_kernarg_preload_length 0
		.amdhsa_user_sgpr_kernarg_preload_offset 0
		.amdhsa_user_sgpr_private_segment_size 0
		.amdhsa_uses_dynamic_stack 0
		.amdhsa_enable_private_segment 0
		.amdhsa_system_sgpr_workgroup_id_x 1
		.amdhsa_system_sgpr_workgroup_id_y 0
		.amdhsa_system_sgpr_workgroup_id_z 0
		.amdhsa_system_sgpr_workgroup_info 0
		.amdhsa_system_vgpr_workitem_id 2
		.amdhsa_next_free_vgpr 256
		.amdhsa_next_free_sgpr 99
		.amdhsa_accum_offset 256
		.amdhsa_reserve_vcc 1
		.amdhsa_float_round_mode_32 0
		.amdhsa_float_round_mode_16_64 0
		.amdhsa_float_denorm_mode_32 3
		.amdhsa_float_denorm_mode_16_64 3
		.amdhsa_dx10_clamp 1
		.amdhsa_ieee_mode 1
		.amdhsa_fp16_overflow 0
		.amdhsa_tg_split 0
		.amdhsa_exception_fp_ieee_invalid_op 0
		.amdhsa_exception_fp_denorm_src 0
		.amdhsa_exception_fp_ieee_div_zero 0
		.amdhsa_exception_fp_ieee_overflow 0
		.amdhsa_exception_fp_ieee_underflow 0
		.amdhsa_exception_fp_ieee_inexact 0
		.amdhsa_exception_int_div_zero 0
	.end_amdhsa_kernel

amdhsa.kernels:
  - .agpr_count:     0
    .args:
      - .offset:         0
        .size:           112
        .value_kind:     by_value
      - .offset:         112
        .size:           4
        .value_kind:     hidden_block_count_x
      - .offset:         116
        .size:           4
        .value_kind:     hidden_block_count_y
      - .offset:         120
        .size:           4
        .value_kind:     hidden_block_count_z
      - .offset:         124
        .size:           2
        .value_kind:     hidden_group_size_x
      - .offset:         126
        .size:           2
        .value_kind:     hidden_group_size_y
      - .offset:         128
        .size:           2
        .value_kind:     hidden_group_size_z
      - .offset:         130
        .size:           2
        .value_kind:     hidden_remainder_x
      - .offset:         132
        .size:           2
        .value_kind:     hidden_remainder_y
      - .offset:         134
        .size:           2
        .value_kind:     hidden_remainder_z
      - .offset:         152
        .size:           8
        .value_kind:     hidden_global_offset_x
      - .offset:         160
        .size:           8
        .value_kind:     hidden_global_offset_y
      - .offset:         168
        .size:           8
        .value_kind:     hidden_global_offset_z
      - .offset:         176
        .size:           2
        .value_kind:     hidden_grid_dims
      - .offset:         200
        .size:           8
        .value_kind:     hidden_multigrid_sync_arg
      - .offset:         232
        .size:           4
        .value_kind:     hidden_dynamic_lds_size
    .group_segment_fixed_size: 0
    .kernarg_segment_align: 8
    .kernarg_segment_size: 368
    .language:       OpenCL C
    .language_version:
      - 2
      - 0
    .max_flat_workgroup_size: 512
    .name:           _Z14fwd_megakernel6Params
    .private_segment_fixed_size: 0
    .sgpr_count:     105
    .sgpr_spill_count: 115
    .symbol:         _Z14fwd_megakernel6Params.kd
    .uniform_work_group_size: 1
    .uses_dynamic_stack: false
    .vgpr_count:     256
    .vgpr_spill_count: 0
    .wavefront_size: 64
